# attention softmax row-max xor16/xor32 shuffles via v_permlane16/32_swap instead of ds_bpermute (6 sites) on top of v020
# baseline (speedup 1.0000x reference)
; #define LAS __attribute__((address_space(3)))
; DI float fast_exp2(float x) { return __builtin_amdgcn_exp2f(x); }
; #define MFMA16(a, b, c) __builtin_amdgcn_mfma_f32_16x16x32_bf16((a), (b), (c), 0, 0, 0)
; DI void at_qk(f32x4 (&s1)[4], f32x4 (&s2)[4], const LAS unsigned char* buf, const bf16x8 q1, const bf16x8 q2, const f32x4 (&ci)[4], int hh, int fr, int fq) {
; #pragma unroll
;     for (int k4 = 0; k4 < 4; ++k4) { const LAS unsigned char* kr = buf + AT_K + (16 * k4 + fr) * 272 + hh * 128 + fq * 16;
;         s1[k4] = MFMA16(ld8l(kr), q1, ci[k4]); s2[k4] = MFMA16(ld8l(kr + 64), q2, ci[k4]); }
; }
; DI void at_exp(f32x4 (&s1)[4], f32x4 (&s2)[4], float& ps1, float& ps2) {
;     f32x4 a1 = (f32x4){0.f, 0.f, 0.f, 0.f}, a2 = a1;
; #pragma unroll
;     for (int k4 = 0; k4 < 4; ++k4) {
; #pragma unroll
;         for (int j = 0; j < 4; ++j) { s1[k4][j] = fast_exp2(s1[k4][j]); s2[k4][j] = fast_exp2(s2[k4][j]); }
;         a1 = a1 + s1[k4]; a2 = a2 + s2[k4]; }
;     ps1 = (a1[0] + a1[1]) + (a1[2] + a1[3]); ps2 = (a2[0] + a2[1]) + (a2[2] + a2[3]);
; }
; template <int VAR>
; DI void attn_tile(AtState& S, const LAS unsigned char* buf, const bf16x8 q1, const bf16x8 q2, int kt, bool diag, int qpos0, int qpos_l, float slope2, float adv, float decay, int hh, int fr, int fq) {
;     ...
;     } else {
;         asm volatile("; attention: fast tile" ::: "memory");
;         at_qk(s1, s2, buf, q1, q2, S.cinit, hh, fr, fq);
;         S.ref += adv;
;         at_exp(s1, s2, ps1, ps2);
;         if (__any(!(ps1 + ps2 < 0x1p60f))) {
;             asm volatile("; attention: bump" ::: "memory");
;             at_qk(s1, s2, buf, q1, q2, S.cinit, hh, fr, fq);
;             float lm = -1e30f;
; #pragma unroll
;             for (int k4 = 0; k4 < 4; ++k4)
; #pragma unroll
;                 for (int j = 0; j < 4; ++j) lm = fmaxf(lm, fmaxf(s1[k4][j], s2[k4][j]));
.LBB0_1376:
	s_add_i32 s27, s26, -1
	s_min_i32 s14, s27, s25
	s_ashr_i32 s15, s14, 31
	s_add_i32 s28, s22, s26
	s_lshl_b64 s[14:15], s[14:15], 18
	s_add_u32 s14, s0, s14
	s_addc_u32 s15, s1, s15
	global_load_dwordx4 v[28:31], v144, s[14:15] offset:1024
	global_load_dwordx4 v[32:35], v144, s[14:15] offset:1536
	global_load_dwordx4 v[36:39], v146, s[14:15] offset:1024
	global_load_dwordx4 v[40:43], v146, s[14:15] offset:1536
	s_cmpk_eq_i32 s28, 0x42
	s_cselect_b64 s[16:17], -1, 0
	s_cmp_eq_u32 s26, 3
	s_cselect_b64 s[14:15], -1, 0
	s_or_b64 s[18:19], s[14:15], s[16:17]
	s_andn2_b64 vcc, exec, s[18:19]
	s_mov_b64 s[18:19], -1
	s_cbranch_vccz .LBB0_1381
	ds_read_b128 v[76:79], v213
	ds_read_b128 v[80:83], v213 offset:64
	ds_read_b128 v[96:99], v213 offset:4352
	ds_read_b128 v[104:107], v213 offset:4416
	ds_read_b128 v[108:111], v213 offset:8704
	ds_read_b128 v[112:115], v213 offset:8768
	ds_read_b128 v[116:119], v213 offset:13056
	ds_read_b128 v[120:123], v213 offset:13120
	s_waitcnt lgkmcnt(7)
	v_mfma_f32_16x16x32_bf16 v[76:79], v[76:79], v[4:7], v[44:47]
	v_add_f32_e32 v215, v205, v214
	s_waitcnt lgkmcnt(6)
	v_mfma_f32_16x16x32_bf16 v[80:83], v[80:83], v[8:11], v[44:47]
	s_waitcnt lgkmcnt(5)
	v_mfma_f32_16x16x32_bf16 v[96:99], v[96:99], v[4:7], v[48:51]
	s_nop 2
	v_exp_f32_e32 v164, v76
	v_exp_f32_e32 v165, v77
	v_exp_f32_e32 v168, v78
	s_waitcnt lgkmcnt(4)
	v_mfma_f32_16x16x32_bf16 v[104:107], v[104:107], v[8:11], v[48:51]
	v_exp_f32_e32 v169, v79
	v_exp_f32_e32 v162, v80
	v_exp_f32_e32 v163, v81
	s_waitcnt lgkmcnt(3)
	v_mfma_f32_16x16x32_bf16 v[108:111], v[108:111], v[4:7], v[52:55]
	v_exp_f32_e32 v166, v82
	v_exp_f32_e32 v167, v83
	v_exp_f32_e32 v172, v96
	s_waitcnt lgkmcnt(2)
	v_mfma_f32_16x16x32_bf16 v[76:79], v[112:115], v[8:11], v[52:55]
	v_exp_f32_e32 v170, v104
	v_exp_f32_e32 v173, v97
	v_exp_f32_e32 v176, v98
	s_waitcnt lgkmcnt(1)
	v_mfma_f32_16x16x32_bf16 v[80:83], v[116:119], v[4:7], v[56:59]
	v_exp_f32_e32 v177, v99
	v_exp_f32_e32 v174, v106
	v_exp_f32_e32 v175, v107
	s_waitcnt lgkmcnt(0)
	v_mfma_f32_16x16x32_bf16 v[112:115], v[120:123], v[8:11], v[56:59]
	v_exp_f32_e32 v171, v105
	v_exp_f32_e32 v180, v108
	v_exp_f32_e32 v178, v76
	v_exp_f32_e32 v181, v109
	v_exp_f32_e32 v179, v77
	v_exp_f32_e32 v184, v110
	v_exp_f32_e32 v185, v111
	v_exp_f32_e32 v182, v78
	v_exp_f32_e32 v183, v79
	v_exp_f32_e32 v188, v80
	v_exp_f32_e32 v186, v112
	v_exp_f32_e32 v189, v81
	v_exp_f32_e32 v192, v82
	v_exp_f32_e32 v193, v83
	v_exp_f32_e32 v190, v114
	v_exp_f32_e32 v191, v115
	v_exp_f32_e32 v187, v113
	v_pk_add_f32 v[124:125], v[164:165], 0 op_sel_hi:[1,0]
	v_pk_add_f32 v[126:127], v[168:169], 0 op_sel_hi:[1,0]
	v_pk_add_f32 v[116:117], v[162:163], 0 op_sel_hi:[1,0]
	v_pk_add_f32 v[118:119], v[166:167], 0 op_sel_hi:[1,0]
	v_pk_add_f32 v[96:97], v[126:127], v[176:177]
	v_pk_add_f32 v[98:99], v[124:125], v[172:173]
	v_pk_add_f32 v[104:105], v[118:119], v[174:175]
	v_pk_add_f32 v[106:107], v[116:117], v[170:171]
	v_pk_add_f32 v[76:77], v[98:99], v[180:181]
	v_pk_add_f32 v[78:79], v[96:97], v[184:185]
	v_pk_add_f32 v[96:97], v[106:107], v[178:179]
	v_pk_add_f32 v[98:99], v[104:105], v[182:183]
	v_pk_add_f32 v[78:79], v[78:79], v[192:193]
	v_pk_add_f32 v[76:77], v[76:77], v[188:189]
	v_pk_add_f32 v[80:81], v[98:99], v[190:191]
	v_pk_add_f32 v[82:83], v[96:97], v[186:187]
	v_mov_b32_e32 v97, v76
	v_mov_b32_e32 v96, v82
	v_mov_b32_e32 v76, v83
	v_mov_b32_e32 v82, v80
	v_mov_b32_e32 v83, v78
	v_mov_b32_e32 v78, v81
	v_pk_add_f32 v[76:77], v[96:97], v[76:77]
	v_pk_add_f32 v[78:79], v[82:83], v[78:79]
	s_nop 0
	v_pk_add_f32 v[194:195], v[76:77], v[78:79]
	s_nop 0
	v_add_f32_e32 v3, v195, v194
	v_cmp_ngt_f32_e32 vcc, s65, v3
	s_cbranch_vccz .LBB0_1394
	ds_read_b128 v[76:79], v213
	ds_read_b128 v[80:83], v213 offset:64
	ds_read_b128 v[96:99], v213 offset:4352
	ds_read_b128 v[104:107], v213 offset:4416
	ds_read_b128 v[108:111], v213 offset:8704
	ds_read_b128 v[112:115], v213 offset:8768
	ds_read_b128 v[116:119], v213 offset:13056
	ds_read_b128 v[120:123], v213 offset:13120
	s_waitcnt lgkmcnt(7)
	v_mfma_f32_16x16x32_bf16 v[76:79], v[76:79], v[4:7], v[44:47]
	s_waitcnt lgkmcnt(6)
	v_mfma_f32_16x16x32_bf16 v[80:83], v[80:83], v[8:11], v[44:47]
	s_nop 5
	v_max_f32_e32 v124, v76, v76
	v_max_f32_e32 v125, v77, v77
	v_max_f32_e32 v126, v79, v79
	s_waitcnt lgkmcnt(5)
	v_mfma_f32_16x16x32_bf16 v[96:99], v[96:99], v[4:7], v[48:51]
	s_waitcnt lgkmcnt(4)
	v_mfma_f32_16x16x32_bf16 v[104:107], v[104:107], v[8:11], v[48:51]
	v_max_f32_e32 v3, v80, v80
	v_max_f32_e32 v3, v124, v3
	v_max_f32_e32 v124, v81, v81
	v_max_f32_e32 v124, v125, v124
	v_max3_f32 v3, v3, s60, v124
	v_max_f32_e32 v124, v82, v82
	v_max_f32_e32 v125, v78, v78
	v_max_f32_e32 v124, v125, v124
	v_max_f32_e32 v125, v83, v83
	v_max_f32_e32 v125, v126, v125
	v_max3_f32 v3, v3, v124, v125
	v_max_f32_e32 v124, v104, v104
	v_max_f32_e32 v125, v96, v96
	v_max_f32_e32 v124, v125, v124
	v_max_f32_e32 v125, v105, v105
	v_max_f32_e32 v126, v97, v97
	s_waitcnt lgkmcnt(3)
	v_mfma_f32_16x16x32_bf16 v[108:111], v[108:111], v[4:7], v[52:55]
	v_max_f32_e32 v125, v126, v125
	v_max3_f32 v3, v3, v124, v125
	v_max_f32_e32 v124, v106, v106
	s_waitcnt lgkmcnt(2)
	v_mfma_f32_16x16x32_bf16 v[112:115], v[112:115], v[8:11], v[52:55]
	v_max_f32_e32 v125, v98, v98
	v_max_f32_e32 v124, v125, v124
	v_max_f32_e32 v125, v107, v107
	v_max_f32_e32 v126, v99, v99
	v_max_f32_e32 v125, v126, v125
	v_max3_f32 v3, v3, v124, v125
	s_nop 1
	v_max_f32_e32 v124, v112, v112
	v_max_f32_e32 v125, v108, v108
	v_max_f32_e32 v124, v125, v124
	v_max_f32_e32 v125, v113, v113
	v_max_f32_e32 v126, v109, v109
	s_waitcnt lgkmcnt(1)
; DI void at_exp(f32x4 (&s1)[4], f32x4 (&s2)[4], float& ps1, float& ps2) {
;     f32x4 a1 = (f32x4){0.f, 0.f, 0.f, 0.f}, a2 = a1;
; #pragma unroll
;     for (int k4 = 0; k4 < 4; ++k4) {
; #pragma unroll
;         for (int j = 0; j < 4; ++j) { s1[k4][j] = fast_exp2(s1[k4][j]); s2[k4][j] = fast_exp2(s2[k4][j]); }
;         a1 = a1 + s1[k4]; a2 = a2 + s2[k4]; }
;     ps1 = (a1[0] + a1[1]) + (a1[2] + a1[3]); ps2 = (a2[0] + a2[1]) + (a2[2] + a2[3]);
; }
; DI void at_pv(AtState& S, const f32x4 (&s1)[4], const f32x4 (&s2)[4], float alpha, float ps1, float ps2, const LAS unsigned char* buf, int hh, int fq, int tq, int tp) {
;     S.l1 = S.l1 * alpha + ps1; S.l2 = S.l2 * alpha + ps2;
; #pragma unroll
;     for (int dt = 0; dt < 4; ++dt) { S.O1[dt] = S.O1[dt] * alpha; S.O2[dt] = S.O2[dt] * alpha; }
;     bf16x8 p1[2], p2[2];
; #pragma unroll
;     for (int s = 0; s < 2; ++s) { p1[s] = packp(s1[2 * s], s1[2 * s + 1]); p2[s] = packp(s2[2 * s], s2[2 * s + 1]); }
; #pragma unroll
;     for (int dh = 0; dh < 2; ++dh) {
;         bf16x8 vt[2][2];
; #pragma unroll
;         for (int d2 = 0; d2 < 2; ++d2)
; #pragma unroll
;             for (int s = 0; s < 2; ++s) { const int dt = 2 * dh + d2; const LAS unsigned char* vr = buf + AT_V + (32 * s + 4 * fq + tq) * 288 + (hh * 64 + 16 * dt + 4 * tp) * 2; vt[d2][s] = cat44(tr4(vr), tr4(vr + 16 * 288)); }
;         __builtin_amdgcn_s_setprio(1);
; #pragma unroll
; template <int VAR>
; DI void attn_tile(AtState& S, const LAS unsigned char* buf, const bf16x8 q1, const bf16x8 q2, int kt, bool diag, int qpos0, int qpos_l, float slope2, float adv, float decay, int hh, int fr, int fq) {
;     ...
;             at_qk(s1, s2, buf, q1, q2, S.cinit, hh, fr, fq);
;             float lm = -1e30f;
; #pragma unroll
;             for (int k4 = 0; k4 < 4; ++k4)
; #pragma unroll
;                 for (int j = 0; j < 4; ++j) lm = fmaxf(lm, fmaxf(s1[k4][j], s2[k4][j]));
;             lm = fmaxf(lm, __shfl_xor(lm, 16)); lm = fmaxf(lm, __shfl_xor(lm, 32));
;             const float bump = fmaxf(lm, 0.f);
;             const float alpha = decay * fast_exp2(-bump); S.ref += bump;
; #pragma unroll
;             for (int k4 = 0; k4 < 4; ++k4) { s1[k4] = s1[k4] - bump; s2[k4] = s2[k4] - bump; S.cinit[k4] = S.cinit[k4] - bump; }
;             at_exp(s1, s2, ps1, ps2);
;             at_pv(S, s1, s2, alpha, ps1, ps2, buf, hh, fq, tq, tp);
	v_mfma_f32_16x16x32_bf16 v[116:119], v[116:119], v[4:7], v[56:59]
	v_max_f32_e32 v125, v126, v125
	v_max3_f32 v3, v3, v124, v125
	v_max_f32_e32 v124, v114, v114
	s_waitcnt lgkmcnt(0)
	v_mfma_f32_16x16x32_bf16 v[120:123], v[120:123], v[8:11], v[56:59]
	v_max_f32_e32 v125, v110, v110
	v_max_f32_e32 v124, v125, v124
	v_max_f32_e32 v125, v115, v115
	v_max_f32_e32 v126, v111, v111
	v_max_f32_e32 v125, v126, v125
	v_max3_f32 v3, v3, v124, v125
	s_nop 1
	v_max_f32_e32 v124, v120, v120
	v_max_f32_e32 v125, v116, v116
	v_max_f32_e32 v124, v125, v124
	v_max_f32_e32 v125, v121, v121
	v_max_f32_e32 v126, v117, v117
	v_max_f32_e32 v125, v126, v125
	v_max3_f32 v3, v3, v124, v125
	v_max_f32_e32 v124, v122, v122
	v_max_f32_e32 v125, v118, v118
	v_max_f32_e32 v124, v125, v124
	v_max_f32_e32 v125, v123, v123
	v_max_f32_e32 v126, v119, v119
	v_max_f32_e32 v125, v126, v125
	v_max3_f32 v3, v3, v124, v125
	v_and_b32_e32 v125, 64, v198
	v_mov_b32_e32 v124, v3
	v_mov_b32_e32 v255, v3
	s_nop 1
	v_permlane16_swap_b32_e32 v124, v255
	s_waitcnt lgkmcnt(0)
	v_max_f32_e32 v3, v124, v255
	v_mov_b32_e32 v124, v3
	v_mov_b32_e32 v255, v3
	s_nop 1
	v_permlane32_swap_b32_e32 v124, v255
	s_waitcnt lgkmcnt(0)
	v_max3_f32 v124, v255, v124, 0
	v_sub_f32_e32 v126, v79, v124
	v_sub_f32_e32 v127, v78, v124
	v_sub_f32_e32 v128, v77, v124
	v_sub_f32_e32 v129, v76, v124
	v_sub_f32_e32 v130, v83, v124
	v_sub_f32_e32 v131, v82, v124
	v_sub_f32_e32 v132, v81, v124
	v_sub_f32_e32 v133, v80, v124
	v_sub_f32_e32 v134, v99, v124
	v_sub_f32_e32 v135, v98, v124
	v_sub_f32_e32 v137, v97, v124
	v_sub_f32_e32 v138, v96, v124
	v_sub_f32_e32 v139, v107, v124
	v_sub_f32_e32 v151, v106, v124
	v_sub_f32_e32 v158, v105, v124
	v_sub_f32_e32 v159, v104, v124
	v_exp_f32_e32 v216, v129
	v_exp_f32_e32 v220, v133
	v_exp_f32_e32 v217, v128
	v_exp_f32_e32 v221, v132
	v_exp_f32_e32 v218, v127
	v_exp_f32_e32 v222, v131
	v_exp_f32_e32 v219, v126
	v_exp_f32_e32 v223, v130
	v_sub_f32_e32 v237, v111, v124
	v_sub_f32_e32 v236, v110, v124
	v_sub_f32_e32 v233, v109, v124
	v_sub_f32_e32 v232, v108, v124
	v_sub_f32_e32 v239, v115, v124
	v_sub_f32_e32 v238, v114, v124
	v_sub_f32_e32 v235, v113, v124
	v_sub_f32_e32 v234, v112, v124
	v_exp_f32_e32 v224, v138
	v_exp_f32_e32 v226, v159
	v_exp_f32_e32 v225, v137
	v_exp_f32_e32 v227, v158
	v_exp_f32_e32 v228, v135
	v_exp_f32_e32 v230, v151
	v_exp_f32_e32 v229, v134
	v_exp_f32_e32 v231, v139
	v_sub_f32_e32 v119, v119, v124
	v_sub_f32_e32 v118, v118, v124
	v_sub_f32_e32 v117, v117, v124
	v_sub_f32_e32 v116, v116, v124
	v_sub_f32_e32 v123, v123, v124
	v_sub_f32_e32 v122, v122, v124
	v_sub_f32_e32 v121, v121, v124
	v_sub_f32_e32 v120, v120, v124
	v_exp_f32_e32 v232, v232
	v_exp_f32_e32 v234, v234
	v_exp_f32_e32 v233, v233
	v_exp_f32_e32 v235, v235
	v_exp_f32_e32 v236, v236
	v_exp_f32_e32 v238, v238
	v_exp_f32_e32 v237, v237
	v_exp_f32_e32 v239, v239
	v_exp_f32_e32 v240, v116
	v_exp_f32_e32 v242, v120
	v_exp_f32_e32 v241, v117
	v_exp_f32_e32 v243, v121
	v_exp_f32_e32 v244, v118
	v_exp_f32_e32 v246, v122
	v_exp_f32_e32 v245, v119
	v_exp_f32_e32 v247, v123
	v_pk_add_f32 v[108:109], v[216:217], 0 op_sel_hi:[1,0]
	v_pk_add_f32 v[110:111], v[218:219], 0 op_sel_hi:[1,0]
	v_pk_add_f32 v[112:113], v[220:221], 0 op_sel_hi:[1,0]
	v_pk_add_f32 v[114:115], v[222:223], 0 op_sel_hi:[1,0]
	v_pk_add_f32 v[110:111], v[228:229], v[110:111]
	v_pk_add_f32 v[108:109], v[224:225], v[108:109]
	v_pk_add_f32 v[114:115], v[230:231], v[114:115]
	v_pk_add_f32 v[112:113], v[226:227], v[112:113]
	v_pk_add_f32 v[108:109], v[232:233], v[108:109]
	v_pk_add_f32 v[110:111], v[236:237], v[110:111]
	v_pk_add_f32 v[112:113], v[234:235], v[112:113]
	v_pk_add_f32 v[114:115], v[238:239], v[114:115]
	v_pk_add_f32 v[110:111], v[244:245], v[110:111]
	v_pk_add_f32 v[108:109], v[240:241], v[108:109]
	v_pk_add_f32 v[114:115], v[246:247], v[114:115]
	v_pk_add_f32 v[112:113], v[242:243], v[112:113]
	v_cvt_pk_bf16_f32 v216, v216, v217
	v_cvt_pk_bf16_f32 v217, v218, v219
	v_cvt_pk_bf16_f32 v218, v224, v225
	v_cvt_pk_bf16_f32 v219, v228, v229
	v_cvt_pk_bf16_f32 v220, v220, v221
	v_cvt_pk_bf16_f32 v221, v222, v223
	v_cvt_pk_bf16_f32 v222, v226, v227
	v_cvt_pk_bf16_f32 v223, v230, v231
	v_cvt_pk_bf16_f32 v224, v232, v233
	v_cvt_pk_bf16_f32 v225, v236, v237
	v_cvt_pk_bf16_f32 v226, v240, v241
	v_cvt_pk_bf16_f32 v227, v244, v245
	v_cvt_pk_bf16_f32 v228, v234, v235
	v_cvt_pk_bf16_f32 v229, v238, v239
	v_cvt_pk_bf16_f32 v230, v242, v243
	v_cvt_pk_bf16_f32 v231, v246, v247
	ds_read_b64_tr_b16 v[232:233], v208 offset:17408
	ds_read_b64_tr_b16 v[236:237], v208 offset:17440
	ds_read_b64_tr_b16 v[234:235], v208 offset:22016
	ds_read_b64_tr_b16 v[240:241], v208 offset:26624
	ds_read_b64_tr_b16 v[242:243], v208 offset:31232
	ds_read_b64_tr_b16 v[238:239], v208 offset:22048
	ds_read_b64_tr_b16 v[244:245], v208 offset:26656
	ds_read_b64_tr_b16 v[246:247], v208 offset:31264
	v_exp_f32_e64 v125, -v124
	v_mov_b32_e32 v116, v112
	v_mov_b32_e32 v117, v108
	v_mov_b32_e32 v108, v113
	v_mov_b32_e32 v112, v114
	v_mov_b32_e32 v113, v110
	v_mov_b32_e32 v110, v115
	v_pk_add_f32 v[108:109], v[116:117], v[108:109]
	v_pk_add_f32 v[110:111], v[112:113], v[110:111]
	v_mul_f32_e32 v136, v150, v125
	v_pk_add_f32 v[108:109], v[108:109], v[110:111]
	v_add_f32_e32 v3, v215, v124
	v_sub_f32_e32 v79, v47, v124
	v_sub_f32_e32 v78, v46, v124
	v_sub_f32_e32 v77, v45, v124
	v_sub_f32_e32 v76, v44, v124
	v_sub_f32_e32 v99, v51, v124
	v_sub_f32_e32 v98, v50, v124
	v_sub_f32_e32 v97, v49, v124
	v_sub_f32_e32 v96, v48, v124
	v_sub_f32_e32 v107, v55, v124
	v_sub_f32_e32 v106, v54, v124
	v_sub_f32_e32 v105, v53, v124
	v_sub_f32_e32 v104, v52, v124
	v_sub_f32_e32 v83, v59, v124
	v_sub_f32_e32 v82, v58, v124
	v_sub_f32_e32 v81, v57, v124
	v_sub_f32_e32 v80, v56, v124
	v_pk_fma_f32 v[158:159], v[156:157], v[136:137], v[108:109] op_sel_hi:[1,0,1]
	v_pk_mul_f32 v[110:111], v[66:67], v[136:137] op_sel_hi:[1,0]
	v_pk_mul_f32 v[108:109], v[64:65], v[136:137] op_sel_hi:[1,0]
	v_pk_mul_f32 v[114:115], v[74:75], v[136:137] op_sel_hi:[1,0]
	v_pk_mul_f32 v[112:113], v[72:73], v[136:137] op_sel_hi:[1,0]
	v_pk_mul_f32 v[118:119], v[62:63], v[136:137] op_sel_hi:[1,0]
	v_pk_mul_f32 v[116:117], v[60:61], v[136:137] op_sel_hi:[1,0]
	v_pk_mul_f32 v[122:123], v[70:71], v[136:137] op_sel_hi:[1,0]
	v_pk_mul_f32 v[120:121], v[68:69], v[136:137] op_sel_hi:[1,0]
	v_pk_mul_f32 v[126:127], v[90:91], v[136:137] op_sel_hi:[1,0]
	v_pk_mul_f32 v[124:125], v[88:89], v[136:137] op_sel_hi:[1,0]
	v_pk_mul_f32 v[130:131], v[102:103], v[136:137] op_sel_hi:[1,0]
	v_pk_mul_f32 v[128:129], v[100:101], v[136:137] op_sel_hi:[1,0]
	v_pk_mul_f32 v[134:135], v[86:87], v[136:137] op_sel_hi:[1,0]
	v_pk_mul_f32 v[132:133], v[84:85], v[136:137] op_sel_hi:[1,0]
	v_pk_mul_f32 v[138:139], v[94:95], v[136:137] op_sel_hi:[1,0]
	v_pk_mul_f32 v[136:137], v[92:93], v[136:137] op_sel_hi:[1,0]
	s_setprio 1
	s_waitcnt lgkmcnt(5)
; #define LAS __attribute__((address_space(3)))
; #define MFMA16(a, b, c) __builtin_amdgcn_mfma_f32_16x16x32_bf16((a), (b), (c), 0, 0, 0)
; DI u32x2 tr4(const LAS unsigned char* p) { return __builtin_bit_cast(u32x2, __builtin_amdgcn_ds_read_tr16_b64_v4i16((LAS v4i16_t*)p)); }
; DI void at_pv(AtState& S, const f32x4 (&s1)[4], const f32x4 (&s2)[4], float alpha, float ps1, float ps2, const LAS unsigned char* buf, int hh, int fq, int tq, int tp) {
;     ...
;     for (int dh = 0; dh < 2; ++dh) {
;         bf16x8 vt[2][2];
; #pragma unroll
;         for (int d2 = 0; d2 < 2; ++d2)
; #pragma unroll
;             for (int s = 0; s < 2; ++s) { const int dt = 2 * dh + d2; const LAS unsigned char* vr = buf + AT_V + (32 * s + 4 * fq + tq) * 288 + (hh * 64 + 16 * dt + 4 * tp) * 2; vt[d2][s] = cat44(tr4(vr), tr4(vr + 16 * 288)); }
;         __builtin_amdgcn_s_setprio(1);
; #pragma unroll
;         for (int s = 0; s < 2; ++s)
; #pragma unroll
;             for (int d2 = 0; d2 < 2; ++d2) { const int dt = 2 * dh + d2; S.O1[dt] = MFMA16(vt[d2][s], p1[s], S.O1[dt]); S.O2[dt] = MFMA16(vt[d2][s], p2[s], S.O2[dt]); }
;         __builtin_amdgcn_s_setprio(0);
;         __builtin_amdgcn_sched_barrier(0);
;     }
	v_mfma_f32_16x16x32_bf16 v[108:111], v[232:235], v[216:219], v[108:111]
	v_mfma_f32_16x16x32_bf16 v[112:115], v[232:235], v[220:223], v[112:115]
	s_waitcnt lgkmcnt(2)
	v_mfma_f32_16x16x32_bf16 v[232:235], v[236:239], v[216:219], v[116:119]
	v_mfma_f32_16x16x32_bf16 v[236:239], v[236:239], v[220:223], v[120:123]
	v_mfma_f32_16x16x32_bf16 v[120:123], v[240:243], v[224:227], v[108:111]
	v_mfma_f32_16x16x32_bf16 v[116:119], v[240:243], v[228:231], v[112:115]
	s_waitcnt lgkmcnt(0)
	v_mfma_f32_16x16x32_bf16 v[112:115], v[244:247], v[224:227], v[232:235]
	v_mfma_f32_16x16x32_bf16 v[108:111], v[244:247], v[228:231], v[236:239]
	s_setprio 0
	s_nop 0
	ds_read_b64_tr_b16 v[232:233], v208 offset:17472
	ds_read_b64_tr_b16 v[236:237], v208 offset:17504
	ds_read_b64_tr_b16 v[234:235], v208 offset:22080
	ds_read_b64_tr_b16 v[238:239], v208 offset:22112
	ds_read_b64_tr_b16 v[240:241], v208 offset:26688
	ds_read_b64_tr_b16 v[242:243], v208 offset:31296
	ds_read_b64_tr_b16 v[246:247], v208 offset:31328
	ds_read_b64_tr_b16 v[244:245], v208 offset:26720
	s_setprio 1
	s_waitcnt lgkmcnt(5)
	v_mfma_f32_16x16x32_bf16 v[124:127], v[232:235], v[216:219], v[124:127]
	v_mfma_f32_16x16x32_bf16 v[128:131], v[232:235], v[220:223], v[128:131]
	s_waitcnt lgkmcnt(4)
	v_mfma_f32_16x16x32_bf16 v[216:219], v[236:239], v[216:219], v[132:135]
	v_mfma_f32_16x16x32_bf16 v[220:223], v[236:239], v[220:223], v[136:139]
	s_waitcnt lgkmcnt(2)
	v_mfma_f32_16x16x32_bf16 v[136:139], v[240:243], v[224:227], v[124:127]
	v_mfma_f32_16x16x32_bf16 v[132:135], v[240:243], v[228:231], v[128:131]
	s_waitcnt lgkmcnt(0)
	v_mfma_f32_16x16x32_bf16 v[128:131], v[244:247], v[224:227], v[216:219]
	v_mfma_f32_16x16x32_bf16 v[124:127], v[244:247], v[228:231], v[220:223]
	s_setprio 0
	s_cbranch_execnz .LBB0_1380

; DI float fast_exp2(float x) { return __builtin_amdgcn_exp2f(x); }
; template <int VAR>
; DI void attn_tile(AtState& S, const LAS unsigned char* buf, const bf16x8 q1, const bf16x8 q2, int kt, bool diag, int qpos0, int qpos_l, float slope2, float adv, float decay, int hh, int fr, int fq) {
;     ...
;     const bool exact = diag || kt == 0;
;     f32x4 s1[4], s2[4]; float ps1, ps2;
;     if (exact) {
;         asm volatile("; attention: exact tile" ::: "memory");
;         { f32x4 z[4];
; #pragma unroll
;           for (int k4 = 0; k4 < 4; ++k4) z[k4] = (f32x4){0.f, 0.f, 0.f, 0.f};
;           at_qk(s1, s2, buf, q1, q2, z, hh, fr, fq); }
;         int ql = qpos_l - 4 * fq; asm volatile("" : "+v"(ql));
;         const float dk = slope2 * (float)(qpos0 - kt * 64);
;         float mx = -1e30f;
; #pragma unroll
;         for (int k4 = 0; k4 < 4; ++k4)
; #pragma unroll
;             for (int j = 0; j < 4; ++j) { const float g = slope2 * (float)(16 * k4 + j - ql); const float bias = diag ? -fabsf(g) : g - dk;
;                 s1[k4][j] += bias; s2[k4][j] += bias; mx = fmaxf(mx, fmaxf(s1[k4][j], s2[k4][j])); }
;         mx = fmaxf(mx, __shfl_xor(mx, 16)); mx = fmaxf(mx, __shfl_xor(mx, 32));
;         const float nref = fmaxf(S.ref, mx);
;         const float alpha = fast_exp2(S.ref - nref); S.ref = nref;
; #pragma unroll
;         for (int k4 = 0; k4 < 4; ++k4) { s1[k4] = s1[k4] - nref; s2[k4] = s2[k4] - nref; }
;         if (kt == 0) { const float c0 = -slope2 * (float)qpos0 - S.ref;
; #pragma unroll
;             for (int k4 = 0; k4 < 4; ++k4)
; #pragma unroll
;                 for (int j = 0; j < 4; ++j) S.cinit[k4][j] = slope2 * (float)(16 * k4 + j - ql) + c0; }
.LBB0_1381:
	s_andn2_b64 vcc, exec, s[18:19]
	s_cbranch_vccnz .LBB0_1385
	ds_read_b128 v[76:79], v213
	ds_read_b128 v[80:83], v213 offset:13120
	v_mov_b32_e32 v3, v206
	v_cvt_f32_i32_e32 v158, s23
	s_waitcnt lgkmcnt(1)
	v_mfma_f32_16x16x32_bf16 v[110:113], v[76:79], v[4:7], 0
	ds_read_b128 v[76:79], v213 offset:64
	s_waitcnt lgkmcnt(1)
	v_mfma_f32_16x16x32_bf16 v[80:83], v[80:83], v[8:11], 0
	s_waitcnt lgkmcnt(0)
	v_mfma_f32_16x16x32_bf16 v[114:117], v[76:79], v[8:11], 0
	ds_read_b128 v[76:79], v213 offset:4352
	s_waitcnt lgkmcnt(0)
	v_mfma_f32_16x16x32_bf16 v[130:133], v[76:79], v[4:7], 0
	ds_read_b128 v[76:79], v213 offset:4416
	s_waitcnt lgkmcnt(0)
	v_mfma_f32_16x16x32_bf16 v[134:137], v[76:79], v[8:11], 0
	ds_read_b128 v[76:79], v213 offset:8704
	s_waitcnt lgkmcnt(0)
	v_mfma_f32_16x16x32_bf16 v[96:99], v[76:79], v[4:7], 0
	ds_read_b128 v[76:79], v213 offset:8768
	s_waitcnt lgkmcnt(0)
	v_mfma_f32_16x16x32_bf16 v[104:107], v[76:79], v[8:11], 0
	ds_read_b128 v[76:79], v213 offset:13056
	s_nop 0
	v_sub_u32_e32 v108, 0, v3
	v_sub_u32_e32 v109, 1, v3
	v_cvt_f32_i32_e32 v109, v109
	v_cvt_f32_i32_e32 v108, v108
	s_waitcnt lgkmcnt(0)
	v_mfma_f32_16x16x32_bf16 v[76:79], v[76:79], v[4:7], 0
	v_mul_f32_e64 v108, v148, v108
	v_mul_f32_e64 v109, v149, v109
	v_fma_f32 v118, -v148, v158, v108
	v_cndmask_b32_e64 v119, v118, -|v108|, s[16:17]
	v_add_f32_e32 v118, v110, v119
	v_add_f32_e32 v119, v114, v119
	v_fma_f32 v114, -v148, v158, v109
	v_cndmask_b32_e64 v114, v114, -|v109|, s[16:17]
	v_add_f32_e32 v121, v111, v114
	v_add_f32_e32 v120, v115, v114
	v_max_f32_e32 v110, v118, v119
	v_max_f32_e32 v111, v121, v120
	v_max3_f32 v114, v110, s60, v111
	v_sub_u32_e32 v110, 2, v3
	v_sub_u32_e32 v111, 3, v3
	v_cvt_f32_i32_e32 v111, v111
	v_cvt_f32_i32_e32 v110, v110
	v_pk_mul_f32 v[110:111], v[148:149], v[110:111]
	s_nop 0
	v_fma_f32 v115, -v148, v158, v110
	v_cndmask_b32_e64 v115, v115, -|v110|, s[16:17]
	v_add_f32_e32 v123, v112, v115
	v_add_f32_e32 v122, v116, v115
	v_fma_f32 v115, -v148, v158, v111
	v_cndmask_b32_e64 v115, v115, -|v111|, s[16:17]
	v_add_f32_e32 v125, v113, v115
	v_add_f32_e32 v124, v117, v115
	v_max_f32_e32 v112, v123, v122
	v_max_f32_e32 v113, v125, v124
	v_max3_f32 v114, v114, v112, v113
	v_sub_u32_e32 v112, 16, v3
	v_sub_u32_e32 v113, 17, v3
	v_cvt_f32_i32_e32 v113, v113
	v_cvt_f32_i32_e32 v112, v112
	v_pk_mul_f32 v[112:113], v[148:149], v[112:113]
	s_nop 0
	v_fma_f32 v115, -v148, v158, v112
	v_fma_f32 v116, -v148, v158, v113
	v_cndmask_b32_e64 v115, v115, -|v112|, s[16:17]
	v_cndmask_b32_e64 v116, v116, -|v113|, s[16:17]
	v_add_f32_e32 v127, v130, v115
	v_add_f32_e32 v126, v134, v115
	v_add_f32_e32 v129, v131, v116
	v_add_f32_e32 v128, v135, v116
	v_max_f32_e32 v115, v127, v126
	v_max_f32_e32 v116, v129, v128
	v_max3_f32 v116, v114, v115, v116
	v_sub_u32_e32 v114, 18, v3
	v_sub_u32_e32 v115, 19, v3
	v_cvt_f32_i32_e32 v115, v115
	v_cvt_f32_i32_e32 v114, v114
	v_pk_mul_f32 v[114:115], v[148:149], v[114:115]
	s_nop 0
	v_fma_f32 v117, -v148, v158, v114
	v_cndmask_b32_e64 v117, v117, -|v114|, s[16:17]
	v_add_f32_e32 v131, v132, v117
	v_fma_f32 v132, -v148, v158, v115
	v_cndmask_b32_e64 v132, v132, -|v115|, s[16:17]
	v_add_f32_e32 v130, v136, v117
	v_add_f32_e32 v133, v133, v132
	v_add_f32_e32 v132, v137, v132
	v_max_f32_e32 v117, v131, v130
	v_max_f32_e32 v134, v133, v132
	v_max3_f32 v136, v116, v117, v134
	v_sub_u32_e32 v116, 32, v3
	v_sub_u32_e32 v117, 33, v3
	v_cvt_f32_i32_e32 v117, v117
	v_cvt_f32_i32_e32 v116, v116
	v_pk_mul_f32 v[116:117], v[148:149], v[116:117]
	s_nop 0
	v_fma_f32 v134, -v148, v158, v116
	v_cndmask_b32_e64 v135, v134, -|v116|, s[16:17]
	v_add_f32_e32 v134, v96, v135
	v_add_f32_e32 v104, v104, v135
	v_fma_f32 v135, -v148, v158, v117
	v_cndmask_b32_e64 v137, v135, -|v117|, s[16:17]
	v_add_f32_e32 v135, v97, v137
	v_add_f32_e32 v105, v105, v137
	v_max_f32_e32 v96, v134, v104
	v_max_f32_e32 v97, v135, v105
	v_max3_f32 v138, v136, v96, v97
	v_sub_u32_e32 v96, 34, v3
	v_sub_u32_e32 v97, 35, v3
	v_cvt_f32_i32_e32 v97, v97
	v_cvt_f32_i32_e32 v96, v96
	v_pk_mul_f32 v[96:97], v[148:149], v[96:97]
	s_nop 0
	v_fma_f32 v136, -v148, v158, v96
	v_cndmask_b32_e64 v137, v136, -|v96|, s[16:17]
	v_add_f32_e32 v136, v98, v137
	v_add_f32_e32 v106, v106, v137
	v_fma_f32 v137, -v148, v158, v97
	v_cndmask_b32_e64 v139, v137, -|v97|, s[16:17]
	v_add_f32_e32 v137, v99, v139
	v_add_f32_e32 v107, v107, v139
	v_max_f32_e32 v98, v136, v106
	v_max_f32_e32 v99, v137, v107
	v_max3_f32 v151, v138, v98, v99
	v_sub_u32_e32 v98, 48, v3
	v_sub_u32_e32 v99, 49, v3
	v_cvt_f32_i32_e32 v99, v99
	v_cvt_f32_i32_e32 v98, v98
	v_pk_mul_f32 v[98:99], v[148:149], v[98:99]
	s_nop 0
	v_fma_f32 v138, -v148, v158, v98
	v_cndmask_b32_e64 v139, v138, -|v98|, s[16:17]
	v_add_f32_e32 v138, v76, v139
	v_add_f32_e32 v80, v80, v139
	v_fma_f32 v139, -v148, v158, v99
	v_cndmask_b32_e64 v159, v139, -|v99|, s[16:17]
	v_add_f32_e32 v139, v77, v159
	v_add_f32_e32 v81, v81, v159
	v_max_f32_e32 v76, v138, v80
	v_max_f32_e32 v77, v139, v81
	v_max3_f32 v159, v151, v76, v77
	v_sub_u32_e32 v76, 50, v3
	v_sub_u32_e32 v3, 51, v3
	v_cvt_f32_i32_e32 v77, v3
	v_cvt_f32_i32_e32 v76, v76
	v_pk_mul_f32 v[76:77], v[148:149], v[76:77]
	s_nop 0
	v_fma_f32 v3, -v148, v158, v76
	v_cndmask_b32_e64 v3, v3, -|v76|, s[16:17]
	v_add_f32_e32 v151, v78, v3
	v_add_f32_e32 v78, v82, v3
	v_fma_f32 v82, -v148, v158, v77
	v_cndmask_b32_e64 v158, v82, -|v77|, s[16:17]
	v_add_f32_e32 v82, v79, v158
	v_add_f32_e32 v79, v83, v158
	v_max_f32_e32 v3, v151, v78
	v_max_f32_e32 v83, v82, v79
	v_and_b32_e32 v158, 64, v198
	v_max3_f32 v3, v159, v3, v83
	v_mov_b32_e32 v83, v3
	v_mov_b32_e32 v255, v3
	s_nop 1
	v_permlane16_swap_b32_e32 v83, v255
	s_waitcnt lgkmcnt(0)
	v_max_f32_e32 v3, v83, v255
	v_mov_b32_e32 v83, v3
	v_mov_b32_e32 v255, v3
	s_nop 1
	v_permlane32_swap_b32_e32 v83, v255
	s_andn2_b64 vcc, exec, s[14:15]
	s_waitcnt lgkmcnt(0)
	v_max3_f32 v3, v214, v255, v83
	s_cbranch_vccnz .LBB0_1384
	v_sub_f32_e32 v56, v207, v3
	v_pk_add_f32 v[46:47], v[110:111], v[56:57] op_sel_hi:[1,0]
	v_pk_add_f32 v[44:45], v[108:109], v[56:57] op_sel_hi:[1,0]
	v_pk_add_f32 v[50:51], v[114:115], v[56:57] op_sel_hi:[1,0]
	v_pk_add_f32 v[48:49], v[112:113], v[56:57] op_sel_hi:[1,0]
	v_pk_add_f32 v[54:55], v[96:97], v[56:57] op_sel_hi:[1,0]
	v_pk_add_f32 v[52:53], v[116:117], v[56:57] op_sel_hi:[1,0]
	v_pk_add_f32 v[58:59], v[76:77], v[56:57] op_sel_hi:[1,0]
	v_pk_add_f32 v[56:57], v[98:99], v[56:57] op_sel_hi:[1,0]

; DI void lds_barrier() { asm volatile("s_waitcnt lgkmcnt(0)" ::: "memory"); __builtin_amdgcn_s_barrier(); asm volatile("" ::: "memory"); }
; template <int VAR>
; DI void attn_tile(AtState& S, const LAS unsigned char* buf, const bf16x8 q1, const bf16x8 q2, int kt, bool diag, int qpos0, int qpos_l, float slope2, float adv, float decay, int hh, int fr, int fq) {
;     ...
;         asm volatile("; attention: fast tile" ::: "memory");
;         at_qk(s1, s2, buf, q1, q2, S.cinit, hh, fr, fq);
;         S.ref += adv;
;         at_exp(s1, s2, ps1, ps2);
;         if (__any(!(ps1 + ps2 < 0x1p60f))) {
;             asm volatile("; attention: bump" ::: "memory");
;             at_qk(s1, s2, buf, q1, q2, S.cinit, hh, fr, fq);
;             float lm = -1e30f;
; #pragma unroll
;             for (int k4 = 0; k4 < 4; ++k4)
; #pragma unroll
;                 for (int j = 0; j < 4; ++j) lm = fmaxf(lm, fmaxf(s1[k4][j], s2[k4][j]));
;             lm = fmaxf(lm, __shfl_xor(lm, 16)); lm = fmaxf(lm, __shfl_xor(lm, 32));
; template <int VAR>
; DI void attn_segment(const Args& a, const Frame& F, int l, int qrow0, int qpos0, int hp, int ntile, int nf32, const float* ck, const float* cv, int prow0) {
;     ...
;         for (int kt = 0; kt < ntile; kt += 2) {
;             atb_issue(rb, pb + (size_t)(kt + 2 < nl ? kt + 2 : nl) * TSTR, voff);
;             attn_tile<VAR>(S, F.lds + (kt & 1) * AT_BUF, q1, q2, kt, kt + 1 == ntile, qpos0, qpos_l, slope2, adv, decay, hh, fr, fq);
;             atb_commit(ra, F.lds + ((kt + 1) & 1) * AT_BUF, tid);
;             lds_barrier();
;             if (kt + 1 >= ntile) break;
;             atb_issue(ra, pb + (size_t)(kt + 3 < nl ? kt + 3 : nl) * TSTR, voff);
;             attn_tile<VAR>(S, F.lds + ((kt + 1) & 1) * AT_BUF, q1, q2, kt + 1, kt + 2 == ntile, qpos0, qpos_l, slope2, adv, decay, hh, fr, fq);
.Lcommit_done_A:
	s_waitcnt lgkmcnt(0)
	s_barrier
	s_add_i32 s14, s26, -2
	s_cmp_ge_i32 s14, s24
	s_mov_b64 s[14:15], -1
	s_cbranch_scc1 .LBB0_1375
	s_min_i32 s14, s26, s25
	s_ashr_i32 s15, s14, 31
	s_lshl_b64 s[14:15], s[14:15], 18
	s_add_u32 s14, s0, s14
	s_addc_u32 s15, s1, s15
	v_lshl_add_u64 v[16:17], s[14:15], 0, v[144:145]
	v_lshl_add_u64 v[24:25], s[14:15], 0, v[146:147]
	global_load_dwordx4 v[12:15], v[16:17], off offset:1024
	s_nop 0
	global_load_dwordx4 v[16:19], v[16:17], off offset:1536
	s_nop 0
	global_load_dwordx4 v[20:23], v[24:25], off offset:1024
	s_nop 0
	global_load_dwordx4 v[24:27], v[24:25], off offset:1536
	s_cmpk_lg_i32 s28, 0x41
	s_mov_b64 s[14:15], -1
	s_cbranch_scc0 .LBB0_1391
	ds_read_b128 v[44:47], v213 offset:35840
	ds_read_b128 v[48:51], v213 offset:35904
	ds_read_b128 v[52:55], v213 offset:40192
	ds_read_b128 v[56:59], v213 offset:40256
	ds_read_b128 v[60:63], v213 offset:44544
	ds_read_b128 v[64:67], v213 offset:44608
	ds_read_b128 v[68:71], v213 offset:48896
	ds_read_b128 v[72:75], v213 offset:48960
	s_waitcnt lgkmcnt(7)
	v_mfma_f32_16x16x32_bf16 v[44:47], v[44:47], v[4:7], v[76:79]
	v_add_f32_e32 v215, v205, v3
	s_waitcnt lgkmcnt(6)
	v_mfma_f32_16x16x32_bf16 v[48:51], v[48:51], v[8:11], v[76:79]
	s_waitcnt lgkmcnt(5)
	v_mfma_f32_16x16x32_bf16 v[52:55], v[52:55], v[4:7], v[96:99]
	s_nop 2
	v_exp_f32_e32 v164, v44
	v_exp_f32_e32 v165, v45
	v_exp_f32_e32 v168, v46
	s_waitcnt lgkmcnt(4)
	v_mfma_f32_16x16x32_bf16 v[56:59], v[56:59], v[8:11], v[96:99]
	v_exp_f32_e32 v169, v47
	v_exp_f32_e32 v162, v48
	v_exp_f32_e32 v163, v49
	s_waitcnt lgkmcnt(3)
	v_mfma_f32_16x16x32_bf16 v[60:63], v[60:63], v[4:7], v[104:107]
	v_exp_f32_e32 v166, v50
	v_exp_f32_e32 v167, v51
	v_exp_f32_e32 v172, v52
	s_waitcnt lgkmcnt(2)
	v_mfma_f32_16x16x32_bf16 v[44:47], v[64:67], v[8:11], v[104:107]
	v_exp_f32_e32 v170, v56
	v_exp_f32_e32 v173, v53
	v_exp_f32_e32 v176, v54
	s_waitcnt lgkmcnt(1)
	v_mfma_f32_16x16x32_bf16 v[48:51], v[68:71], v[4:7], v[80:83]
	v_exp_f32_e32 v177, v55
	v_exp_f32_e32 v174, v58
	v_exp_f32_e32 v175, v59
	s_waitcnt lgkmcnt(0)
	v_mfma_f32_16x16x32_bf16 v[64:67], v[72:75], v[8:11], v[80:83]
	v_exp_f32_e32 v171, v57
	v_exp_f32_e32 v180, v60
	v_exp_f32_e32 v178, v44
	v_exp_f32_e32 v181, v61
	v_exp_f32_e32 v179, v45
	v_exp_f32_e32 v184, v62
	v_exp_f32_e32 v185, v63
	v_exp_f32_e32 v182, v46
	v_exp_f32_e32 v183, v47
	v_exp_f32_e32 v188, v48
	v_exp_f32_e32 v186, v64
	v_exp_f32_e32 v189, v49
	v_exp_f32_e32 v192, v50
	v_exp_f32_e32 v193, v51
	v_exp_f32_e32 v190, v66
	v_exp_f32_e32 v191, v67
	v_exp_f32_e32 v187, v65
	v_pk_add_f32 v[84:85], v[164:165], 0 op_sel_hi:[1,0]
	v_pk_add_f32 v[86:87], v[168:169], 0 op_sel_hi:[1,0]
	v_pk_add_f32 v[68:69], v[162:163], 0 op_sel_hi:[1,0]
	v_pk_add_f32 v[70:71], v[166:167], 0 op_sel_hi:[1,0]
	v_pk_add_f32 v[52:53], v[86:87], v[176:177]
	v_pk_add_f32 v[54:55], v[84:85], v[172:173]
	v_pk_add_f32 v[56:57], v[70:71], v[174:175]
	v_pk_add_f32 v[58:59], v[68:69], v[170:171]
	v_pk_add_f32 v[44:45], v[54:55], v[180:181]
	v_pk_add_f32 v[46:47], v[52:53], v[184:185]
	v_pk_add_f32 v[52:53], v[58:59], v[178:179]
	v_pk_add_f32 v[54:55], v[56:57], v[182:183]
	v_pk_add_f32 v[46:47], v[46:47], v[192:193]
	v_pk_add_f32 v[44:45], v[44:45], v[188:189]
	v_pk_add_f32 v[48:49], v[54:55], v[190:191]
	v_pk_add_f32 v[50:51], v[52:53], v[186:187]
	v_mov_b32_e32 v53, v44
	v_mov_b32_e32 v52, v50
	v_mov_b32_e32 v44, v51
	v_mov_b32_e32 v50, v48
	v_mov_b32_e32 v51, v46
	v_mov_b32_e32 v46, v49
	v_pk_add_f32 v[44:45], v[52:53], v[44:45]
	v_pk_add_f32 v[46:47], v[50:51], v[46:47]
	s_nop 0
	v_pk_add_f32 v[194:195], v[44:45], v[46:47]
	s_nop 0
	v_add_f32_e32 v44, v195, v194
	v_cmp_ngt_f32_e32 vcc, s65, v44
	s_cbranch_vccz .LBB0_1395
	ds_read_b128 v[44:47], v213 offset:35840
	ds_read_b128 v[48:51], v213 offset:35904
	ds_read_b128 v[52:55], v213 offset:40192
	ds_read_b128 v[56:59], v213 offset:40256
	ds_read_b128 v[60:63], v213 offset:44544
	ds_read_b128 v[64:67], v213 offset:44608
	ds_read_b128 v[68:71], v213 offset:48896
	ds_read_b128 v[72:75], v213 offset:48960
	s_waitcnt lgkmcnt(7)
	v_mfma_f32_16x16x32_bf16 v[44:47], v[44:47], v[4:7], v[76:79]
	s_waitcnt lgkmcnt(6)
	v_mfma_f32_16x16x32_bf16 v[48:51], v[48:51], v[8:11], v[76:79]
	s_nop 5
	v_max_f32_e32 v85, v44, v44
	v_max_f32_e32 v86, v45, v45
	v_max_f32_e32 v87, v47, v47
	s_waitcnt lgkmcnt(5)
	v_mfma_f32_16x16x32_bf16 v[52:55], v[52:55], v[4:7], v[96:99]
	s_waitcnt lgkmcnt(4)
	v_mfma_f32_16x16x32_bf16 v[56:59], v[56:59], v[8:11], v[96:99]
	v_max_f32_e32 v84, v48, v48
	v_max_f32_e32 v84, v85, v84
	v_max_f32_e32 v85, v49, v49
	v_max_f32_e32 v85, v86, v85
	v_max3_f32 v84, v84, s60, v85
	v_max_f32_e32 v85, v50, v50
	v_max_f32_e32 v86, v46, v46
	v_max_f32_e32 v85, v86, v85
	v_max_f32_e32 v86, v51, v51
	v_max_f32_e32 v86, v87, v86
	v_max3_f32 v84, v84, v85, v86
	v_max_f32_e32 v85, v56, v56
	v_max_f32_e32 v86, v52, v52
	v_max_f32_e32 v85, v86, v85
	v_max_f32_e32 v86, v57, v57
	v_max_f32_e32 v87, v53, v53
	s_waitcnt lgkmcnt(3)
	v_mfma_f32_16x16x32_bf16 v[60:63], v[60:63], v[4:7], v[104:107]
	v_max_f32_e32 v86, v87, v86
	v_max3_f32 v84, v84, v85, v86
	v_max_f32_e32 v85, v58, v58
	s_waitcnt lgkmcnt(2)
	v_mfma_f32_16x16x32_bf16 v[64:67], v[64:67], v[8:11], v[104:107]
	v_max_f32_e32 v86, v54, v54
	v_max_f32_e32 v85, v86, v85
	v_max_f32_e32 v86, v59, v59
	v_max_f32_e32 v87, v55, v55
	v_max_f32_e32 v86, v87, v86
	v_max3_f32 v84, v84, v85, v86
	s_nop 1
	v_max_f32_e32 v85, v64, v64
	v_max_f32_e32 v86, v60, v60
	v_max_f32_e32 v85, v86, v85
	v_max_f32_e32 v86, v65, v65
	v_max_f32_e32 v87, v61, v61
	s_waitcnt lgkmcnt(1)
; DI void at_exp(f32x4 (&s1)[4], f32x4 (&s2)[4], float& ps1, float& ps2) {
;     f32x4 a1 = (f32x4){0.f, 0.f, 0.f, 0.f}, a2 = a1;
; #pragma unroll
;     for (int k4 = 0; k4 < 4; ++k4) {
; #pragma unroll
;         for (int j = 0; j < 4; ++j) { s1[k4][j] = fast_exp2(s1[k4][j]); s2[k4][j] = fast_exp2(s2[k4][j]); }
;         a1 = a1 + s1[k4]; a2 = a2 + s2[k4]; }
;     ps1 = (a1[0] + a1[1]) + (a1[2] + a1[3]); ps2 = (a2[0] + a2[1]) + (a2[2] + a2[3]);
; }
; DI void at_pv(AtState& S, const f32x4 (&s1)[4], const f32x4 (&s2)[4], float alpha, float ps1, float ps2, const LAS unsigned char* buf, int hh, int fq, int tq, int tp) {
;     S.l1 = S.l1 * alpha + ps1; S.l2 = S.l2 * alpha + ps2;
; #pragma unroll
;     for (int dt = 0; dt < 4; ++dt) { S.O1[dt] = S.O1[dt] * alpha; S.O2[dt] = S.O2[dt] * alpha; }
;     bf16x8 p1[2], p2[2];
; #pragma unroll
;     for (int s = 0; s < 2; ++s) { p1[s] = packp(s1[2 * s], s1[2 * s + 1]); p2[s] = packp(s2[2 * s], s2[2 * s + 1]); }
; #pragma unroll
;     for (int dh = 0; dh < 2; ++dh) {
;         bf16x8 vt[2][2];
; #pragma unroll
;         for (int d2 = 0; d2 < 2; ++d2)
; #pragma unroll
;             for (int s = 0; s < 2; ++s) { const int dt = 2 * dh + d2; const LAS unsigned char* vr = buf + AT_V + (32 * s + 4 * fq + tq) * 288 + (hh * 64 + 16 * dt + 4 * tp) * 2; vt[d2][s] = cat44(tr4(vr), tr4(vr + 16 * 288)); }
;         __builtin_amdgcn_s_setprio(1);
; #pragma unroll
; template <int VAR>
; DI void attn_tile(AtState& S, const LAS unsigned char* buf, const bf16x8 q1, const bf16x8 q2, int kt, bool diag, int qpos0, int qpos_l, float slope2, float adv, float decay, int hh, int fr, int fq) {
;     ...
;             at_qk(s1, s2, buf, q1, q2, S.cinit, hh, fr, fq);
;             float lm = -1e30f;
; #pragma unroll
;             for (int k4 = 0; k4 < 4; ++k4)
; #pragma unroll
;                 for (int j = 0; j < 4; ++j) lm = fmaxf(lm, fmaxf(s1[k4][j], s2[k4][j]));
;             lm = fmaxf(lm, __shfl_xor(lm, 16)); lm = fmaxf(lm, __shfl_xor(lm, 32));
;             const float bump = fmaxf(lm, 0.f);
;             const float alpha = decay * fast_exp2(-bump); S.ref += bump;
; #pragma unroll
;             for (int k4 = 0; k4 < 4; ++k4) { s1[k4] = s1[k4] - bump; s2[k4] = s2[k4] - bump; S.cinit[k4] = S.cinit[k4] - bump; }
;             at_exp(s1, s2, ps1, ps2);
;             at_pv(S, s1, s2, alpha, ps1, ps2, buf, hh, fq, tq, tp);
	v_mfma_f32_16x16x32_bf16 v[68:71], v[68:71], v[4:7], v[80:83]
	v_max_f32_e32 v86, v87, v86
	v_max3_f32 v84, v84, v85, v86
	v_max_f32_e32 v85, v66, v66
	s_waitcnt lgkmcnt(0)
	v_mfma_f32_16x16x32_bf16 v[72:75], v[72:75], v[8:11], v[80:83]
	v_max_f32_e32 v86, v62, v62
	v_max_f32_e32 v85, v86, v85
	v_max_f32_e32 v86, v67, v67
	v_max_f32_e32 v87, v63, v63
	v_max_f32_e32 v86, v87, v86
	v_max3_f32 v84, v84, v85, v86
	s_nop 1
	v_max_f32_e32 v85, v72, v72
	v_max_f32_e32 v86, v68, v68
	v_max_f32_e32 v85, v86, v85
	v_max_f32_e32 v86, v73, v73
	v_max_f32_e32 v87, v69, v69
	v_max_f32_e32 v86, v87, v86
	v_max3_f32 v84, v84, v85, v86
	v_max_f32_e32 v85, v74, v74
	v_max_f32_e32 v86, v70, v70
	v_max_f32_e32 v85, v86, v85
	v_max_f32_e32 v86, v75, v75
	v_max_f32_e32 v87, v71, v71
	v_max_f32_e32 v86, v87, v86
	v_max3_f32 v84, v84, v85, v86
	v_and_b32_e32 v86, 64, v198
	v_mov_b32_e32 v85, v84
	v_mov_b32_e32 v255, v84
	s_nop 1
	v_permlane16_swap_b32_e32 v85, v255
	s_waitcnt lgkmcnt(0)
	v_max_f32_e32 v84, v85, v255
	v_mov_b32_e32 v85, v84
	v_mov_b32_e32 v255, v84
	s_nop 1
	v_permlane32_swap_b32_e32 v85, v255
	s_waitcnt lgkmcnt(0)
	v_max3_f32 v84, v255, v85, 0
	v_sub_f32_e32 v86, v47, v84
	v_sub_f32_e32 v87, v46, v84
	v_sub_f32_e32 v88, v45, v84
	v_sub_f32_e32 v89, v44, v84
	v_sub_f32_e32 v90, v51, v84
	v_sub_f32_e32 v91, v50, v84
	v_sub_f32_e32 v92, v49, v84
	v_sub_f32_e32 v93, v48, v84
	v_sub_f32_e32 v94, v55, v84
	v_sub_f32_e32 v95, v54, v84
	v_sub_f32_e32 v101, v53, v84
	v_sub_f32_e32 v102, v52, v84
	v_sub_f32_e32 v103, v59, v84
	v_sub_f32_e32 v151, v58, v84
	v_sub_f32_e32 v156, v57, v84
	v_sub_f32_e32 v157, v56, v84
	v_exp_f32_e32 v216, v89
	v_exp_f32_e32 v220, v93
	v_exp_f32_e32 v217, v88
	v_exp_f32_e32 v221, v92
	v_exp_f32_e32 v218, v87
	v_exp_f32_e32 v222, v91
	v_exp_f32_e32 v219, v86
	v_exp_f32_e32 v223, v90
	v_sub_f32_e32 v237, v63, v84
	v_sub_f32_e32 v236, v62, v84
	v_sub_f32_e32 v233, v61, v84
	v_sub_f32_e32 v232, v60, v84
	v_sub_f32_e32 v239, v67, v84
	v_sub_f32_e32 v238, v66, v84
	v_sub_f32_e32 v235, v65, v84
	v_sub_f32_e32 v234, v64, v84
	v_exp_f32_e32 v224, v102
	v_exp_f32_e32 v226, v157
	v_exp_f32_e32 v225, v101
	v_exp_f32_e32 v227, v156
	v_exp_f32_e32 v228, v95
	v_exp_f32_e32 v230, v151
	v_exp_f32_e32 v229, v94
	v_exp_f32_e32 v231, v103
	v_sub_f32_e32 v71, v71, v84
	v_sub_f32_e32 v70, v70, v84
	v_sub_f32_e32 v69, v69, v84
	v_sub_f32_e32 v68, v68, v84
	v_sub_f32_e32 v75, v75, v84
	v_sub_f32_e32 v74, v74, v84
	v_sub_f32_e32 v73, v73, v84
	v_sub_f32_e32 v72, v72, v84
	v_exp_f32_e32 v232, v232
	v_exp_f32_e32 v234, v234
	v_exp_f32_e32 v233, v233
	v_exp_f32_e32 v235, v235
	v_exp_f32_e32 v236, v236
	v_exp_f32_e32 v238, v238
	v_exp_f32_e32 v237, v237
	v_exp_f32_e32 v239, v239
	v_exp_f32_e32 v240, v68
	v_exp_f32_e32 v242, v72
	v_exp_f32_e32 v241, v69
	v_exp_f32_e32 v243, v73
	v_exp_f32_e32 v244, v70
	v_exp_f32_e32 v246, v74
	v_exp_f32_e32 v245, v71
	v_exp_f32_e32 v247, v75
	v_pk_add_f32 v[60:61], v[216:217], 0 op_sel_hi:[1,0]
	v_pk_add_f32 v[62:63], v[218:219], 0 op_sel_hi:[1,0]
	v_pk_add_f32 v[64:65], v[220:221], 0 op_sel_hi:[1,0]
	v_pk_add_f32 v[66:67], v[222:223], 0 op_sel_hi:[1,0]
	v_pk_add_f32 v[62:63], v[228:229], v[62:63]
	v_pk_add_f32 v[60:61], v[224:225], v[60:61]
	v_pk_add_f32 v[66:67], v[230:231], v[66:67]
	v_pk_add_f32 v[64:65], v[226:227], v[64:65]
	v_pk_add_f32 v[60:61], v[232:233], v[60:61]
	v_pk_add_f32 v[62:63], v[236:237], v[62:63]
	v_pk_add_f32 v[64:65], v[234:235], v[64:65]
	v_pk_add_f32 v[66:67], v[238:239], v[66:67]
	v_pk_add_f32 v[62:63], v[244:245], v[62:63]
	v_pk_add_f32 v[60:61], v[240:241], v[60:61]
	v_pk_add_f32 v[66:67], v[246:247], v[66:67]
	v_pk_add_f32 v[64:65], v[242:243], v[64:65]
	v_cvt_pk_bf16_f32 v216, v216, v217
	v_cvt_pk_bf16_f32 v217, v218, v219
	v_cvt_pk_bf16_f32 v218, v224, v225
	v_cvt_pk_bf16_f32 v219, v228, v229
	v_cvt_pk_bf16_f32 v220, v220, v221
	v_cvt_pk_bf16_f32 v221, v222, v223
	v_cvt_pk_bf16_f32 v222, v226, v227
	v_cvt_pk_bf16_f32 v223, v230, v231
	v_cvt_pk_bf16_f32 v224, v232, v233
	v_cvt_pk_bf16_f32 v225, v236, v237
	v_cvt_pk_bf16_f32 v226, v240, v241
	v_cvt_pk_bf16_f32 v227, v244, v245
	v_cvt_pk_bf16_f32 v228, v234, v235
	v_cvt_pk_bf16_f32 v229, v238, v239
	v_cvt_pk_bf16_f32 v230, v242, v243
	v_cvt_pk_bf16_f32 v231, v246, v247
	ds_read_b64_tr_b16 v[232:233], v208 offset:53248
	ds_read_b64_tr_b16 v[236:237], v208 offset:53280
	ds_read_b64_tr_b16 v[234:235], v208 offset:57856
	ds_read_b64_tr_b16 v[240:241], v208 offset:62464
	ds_read_b64_tr_b16 v[242:243], v209 offset:4608
	ds_read_b64_tr_b16 v[238:239], v208 offset:57888
	ds_read_b64_tr_b16 v[244:245], v208 offset:62496
	ds_read_b64_tr_b16 v[246:247], v210 offset:4608
	v_exp_f32_e64 v85, -v84
	v_mov_b32_e32 v68, v64
	v_mov_b32_e32 v69, v60
	v_mov_b32_e32 v60, v65
	v_mov_b32_e32 v64, v66
	v_mov_b32_e32 v65, v62
	v_mov_b32_e32 v62, v67
	v_pk_add_f32 v[60:61], v[68:69], v[60:61]
	v_pk_add_f32 v[62:63], v[64:65], v[62:63]
	v_mul_f32_e32 v100, v150, v85
	v_pk_add_f32 v[60:61], v[60:61], v[62:63]
	v_add_f32_e32 v214, v215, v84
	v_sub_f32_e32 v47, v79, v84
	v_sub_f32_e32 v46, v78, v84
	v_sub_f32_e32 v45, v77, v84
	v_sub_f32_e32 v44, v76, v84
	v_sub_f32_e32 v51, v99, v84
	v_sub_f32_e32 v50, v98, v84
	v_sub_f32_e32 v49, v97, v84
	v_sub_f32_e32 v48, v96, v84
	v_sub_f32_e32 v55, v107, v84
	v_sub_f32_e32 v54, v106, v84
	v_sub_f32_e32 v53, v105, v84
	v_sub_f32_e32 v52, v104, v84
	v_sub_f32_e32 v59, v83, v84
	v_sub_f32_e32 v58, v82, v84
	v_sub_f32_e32 v57, v81, v84
	v_sub_f32_e32 v56, v80, v84
	v_pk_fma_f32 v[156:157], v[158:159], v[100:101], v[60:61] op_sel_hi:[1,0,1]
	v_pk_mul_f32 v[62:63], v[122:123], v[100:101] op_sel_hi:[1,0]
	v_pk_mul_f32 v[60:61], v[120:121], v[100:101] op_sel_hi:[1,0]
	v_pk_mul_f32 v[66:67], v[118:119], v[100:101] op_sel_hi:[1,0]
	v_pk_mul_f32 v[64:65], v[116:117], v[100:101] op_sel_hi:[1,0]
	v_pk_mul_f32 v[70:71], v[114:115], v[100:101] op_sel_hi:[1,0]
	v_pk_mul_f32 v[68:69], v[112:113], v[100:101] op_sel_hi:[1,0]
	v_pk_mul_f32 v[74:75], v[110:111], v[100:101] op_sel_hi:[1,0]
	v_pk_mul_f32 v[72:73], v[108:109], v[100:101] op_sel_hi:[1,0]
	v_pk_mul_f32 v[86:87], v[138:139], v[100:101] op_sel_hi:[1,0]
	v_pk_mul_f32 v[84:85], v[136:137], v[100:101] op_sel_hi:[1,0]
	v_pk_mul_f32 v[90:91], v[134:135], v[100:101] op_sel_hi:[1,0]
	v_pk_mul_f32 v[88:89], v[132:133], v[100:101] op_sel_hi:[1,0]
	v_pk_mul_f32 v[94:95], v[130:131], v[100:101] op_sel_hi:[1,0]
	v_pk_mul_f32 v[92:93], v[128:129], v[100:101] op_sel_hi:[1,0]
	v_pk_mul_f32 v[102:103], v[126:127], v[100:101] op_sel_hi:[1,0]
	v_pk_mul_f32 v[100:101], v[124:125], v[100:101] op_sel_hi:[1,0]
	s_setprio 1
	s_waitcnt lgkmcnt(5)
; #define LAS __attribute__((address_space(3)))
; #define MFMA16(a, b, c) __builtin_amdgcn_mfma_f32_16x16x32_bf16((a), (b), (c), 0, 0, 0)
; DI u32x2 tr4(const LAS unsigned char* p) { return __builtin_bit_cast(u32x2, __builtin_amdgcn_ds_read_tr16_b64_v4i16((LAS v4i16_t*)p)); }
; DI void at_pv(AtState& S, const f32x4 (&s1)[4], const f32x4 (&s2)[4], float alpha, float ps1, float ps2, const LAS unsigned char* buf, int hh, int fq, int tq, int tp) {
;     ...
;     for (int dh = 0; dh < 2; ++dh) {
;         bf16x8 vt[2][2];
; #pragma unroll
;         for (int d2 = 0; d2 < 2; ++d2)
; #pragma unroll
;             for (int s = 0; s < 2; ++s) { const int dt = 2 * dh + d2; const LAS unsigned char* vr = buf + AT_V + (32 * s + 4 * fq + tq) * 288 + (hh * 64 + 16 * dt + 4 * tp) * 2; vt[d2][s] = cat44(tr4(vr), tr4(vr + 16 * 288)); }
;         __builtin_amdgcn_s_setprio(1);
; #pragma unroll
;         for (int s = 0; s < 2; ++s)
; #pragma unroll
;             for (int d2 = 0; d2 < 2; ++d2) { const int dt = 2 * dh + d2; S.O1[dt] = MFMA16(vt[d2][s], p1[s], S.O1[dt]); S.O2[dt] = MFMA16(vt[d2][s], p2[s], S.O2[dt]); }
;         __builtin_amdgcn_s_setprio(0);
;         __builtin_amdgcn_sched_barrier(0);
;     }
	v_mfma_f32_16x16x32_bf16 v[60:63], v[232:235], v[216:219], v[60:63]
	v_mfma_f32_16x16x32_bf16 v[232:235], v[232:235], v[220:223], v[64:67]
	s_waitcnt lgkmcnt(2)
	v_mfma_f32_16x16x32_bf16 v[68:71], v[236:239], v[216:219], v[68:71]
	v_mfma_f32_16x16x32_bf16 v[236:239], v[236:239], v[220:223], v[72:75]
	v_mfma_f32_16x16x32_bf16 v[64:67], v[240:243], v[224:227], v[60:63]
	v_mfma_f32_16x16x32_bf16 v[72:75], v[240:243], v[228:231], v[232:235]
	s_waitcnt lgkmcnt(0)
	v_mfma_f32_16x16x32_bf16 v[60:63], v[244:247], v[224:227], v[68:71]
	v_mfma_f32_16x16x32_bf16 v[68:71], v[244:247], v[228:231], v[236:239]
	s_setprio 0
	ds_read_b64_tr_b16 v[232:233], v208 offset:53312
	s_nop 0
	ds_read_b64_tr_b16 v[236:237], v208 offset:53344
	ds_read_b64_tr_b16 v[234:235], v208 offset:57920
	ds_read_b64_tr_b16 v[238:239], v208 offset:57952
	ds_read_b64_tr_b16 v[240:241], v208 offset:62528
	ds_read_b64_tr_b16 v[242:243], v211 offset:4608
	ds_read_b64_tr_b16 v[246:247], v212 offset:4608
	ds_read_b64_tr_b16 v[244:245], v208 offset:62560
	s_setprio 1
	s_waitcnt lgkmcnt(5)
	v_mfma_f32_16x16x32_bf16 v[84:87], v[232:235], v[216:219], v[84:87]
	v_mfma_f32_16x16x32_bf16 v[232:235], v[232:235], v[220:223], v[88:91]
	s_waitcnt lgkmcnt(4)
	v_mfma_f32_16x16x32_bf16 v[92:95], v[236:239], v[216:219], v[92:95]
	v_mfma_f32_16x16x32_bf16 v[216:219], v[236:239], v[220:223], v[100:103]
	s_waitcnt lgkmcnt(2)
	v_mfma_f32_16x16x32_bf16 v[88:91], v[240:243], v[224:227], v[84:87]
	v_mfma_f32_16x16x32_bf16 v[100:103], v[240:243], v[228:231], v[232:235]
	s_waitcnt lgkmcnt(0)
	v_mfma_f32_16x16x32_bf16 v[84:87], v[244:247], v[224:227], v[92:95]
	v_mfma_f32_16x16x32_bf16 v[92:95], v[244:247], v[228:231], v[216:219]
	s_setprio 0
	s_cbranch_execnz .LBB0_1390

; template <int VAR>
; DI void attn_tile(AtState& S, const LAS unsigned char* buf, const bf16x8 q1, const bf16x8 q2, int kt, bool diag, int qpos0, int qpos_l, float slope2, float adv, float decay, int hh, int fr, int fq) {
;     ...
;         asm volatile("; attention: exact tile" ::: "memory");
;         { f32x4 z[4];
; #pragma unroll
;           for (int k4 = 0; k4 < 4; ++k4) z[k4] = (f32x4){0.f, 0.f, 0.f, 0.f};
;           at_qk(s1, s2, buf, q1, q2, z, hh, fr, fq); }
;         int ql = qpos_l - 4 * fq; asm volatile("" : "+v"(ql));
;         const float dk = slope2 * (float)(qpos0 - kt * 64);
;         float mx = -1e30f;
; #pragma unroll
;         for (int k4 = 0; k4 < 4; ++k4)
; #pragma unroll
;             for (int j = 0; j < 4; ++j) { const float g = slope2 * (float)(16 * k4 + j - ql); const float bias = diag ? -fabsf(g) : g - dk;
;                 s1[k4][j] += bias; s2[k4][j] += bias; mx = fmaxf(mx, fmaxf(s1[k4][j], s2[k4][j])); }
;         mx = fmaxf(mx, __shfl_xor(mx, 16)); mx = fmaxf(mx, __shfl_xor(mx, 32));
.LBB0_1391:
	s_andn2_b64 vcc, exec, s[14:15]
	s_cbranch_vccnz .LBB0_1393
	ds_read_b128 v[44:47], v213 offset:35840
	ds_read_b128 v[48:51], v213 offset:35904
	v_mov_b32_e32 v86, v206
	ds_read_b128 v[52:55], v213 offset:40192
	ds_read_b128 v[56:59], v213 offset:40256
	ds_read_b128 v[60:63], v213 offset:44544
	ds_read_b128 v[64:67], v213 offset:44608
	ds_read_b128 v[68:71], v213 offset:48896
	ds_read_b128 v[72:75], v213 offset:48960
	s_waitcnt lgkmcnt(7)
	v_mfma_f32_16x16x32_bf16 v[44:47], v[44:47], v[4:7], 0
	v_sub_u32_e32 v84, 0, v86
	v_sub_u32_e32 v85, 1, v86
	v_cvt_f32_i32_e32 v85, v85
	v_cvt_f32_i32_e32 v84, v84
	s_waitcnt lgkmcnt(6)
	v_mfma_f32_16x16x32_bf16 v[48:51], v[48:51], v[8:11], 0
	v_mul_f32_e64 v84, v148, v84
	v_mul_f32_e64 v85, v149, v85
	v_and_b32_e32 v85, 0x7fffffff, v85
	v_and_b32_e32 v84, 0x7fffffff, v84
	s_nop 3
	v_pk_add_f32 v[48:49], v[48:49], v[84:85] neg_lo:[0,1] neg_hi:[0,1]
	v_pk_add_f32 v[44:45], v[44:45], v[84:85] neg_lo:[0,1] neg_hi:[0,1]
	v_sub_u32_e32 v84, 2, v86
	v_sub_u32_e32 v85, 3, v86
	v_cvt_f32_i32_e32 v85, v85
	v_cvt_f32_i32_e32 v84, v84
	s_waitcnt lgkmcnt(5)
	v_mfma_f32_16x16x32_bf16 v[52:55], v[52:55], v[4:7], 0
	v_max_f32_e32 v87, v44, v48
	v_max_f32_e32 v88, v45, v49
	v_pk_mul_f32 v[84:85], v[148:149], v[84:85]
	s_waitcnt lgkmcnt(4)
	v_mfma_f32_16x16x32_bf16 v[56:59], v[56:59], v[8:11], 0
	v_and_b32_e32 v85, 0x7fffffff, v85
	v_and_b32_e32 v84, 0x7fffffff, v84
	v_pk_add_f32 v[50:51], v[50:51], v[84:85] neg_lo:[0,1] neg_hi:[0,1]
	v_pk_add_f32 v[46:47], v[46:47], v[84:85] neg_lo:[0,1] neg_hi:[0,1]
	v_sub_u32_e32 v84, 16, v86
	v_sub_u32_e32 v85, 17, v86
	v_cvt_f32_i32_e32 v85, v85
	v_cvt_f32_i32_e32 v84, v84
	s_waitcnt lgkmcnt(3)
	v_mfma_f32_16x16x32_bf16 v[60:63], v[60:63], v[4:7], 0
	v_max3_f32 v87, v87, s60, v88
	v_max_f32_e32 v88, v46, v50
	v_pk_mul_f32 v[84:85], v[148:149], v[84:85]
	s_waitcnt lgkmcnt(2)
	v_mfma_f32_16x16x32_bf16 v[64:67], v[64:67], v[8:11], 0
	v_and_b32_e32 v85, 0x7fffffff, v85
	v_and_b32_e32 v84, 0x7fffffff, v84
	v_pk_add_f32 v[56:57], v[56:57], v[84:85] neg_lo:[0,1] neg_hi:[0,1]
	v_pk_add_f32 v[52:53], v[52:53], v[84:85] neg_lo:[0,1] neg_hi:[0,1]
	v_sub_u32_e32 v84, 18, v86
	v_sub_u32_e32 v85, 19, v86
	v_cvt_f32_i32_e32 v85, v85
	v_cvt_f32_i32_e32 v84, v84
	s_waitcnt lgkmcnt(1)
	v_mfma_f32_16x16x32_bf16 v[68:71], v[68:71], v[4:7], 0
	v_max_f32_e32 v89, v47, v51
	v_max3_f32 v87, v87, v88, v89
	v_pk_mul_f32 v[84:85], v[148:149], v[84:85]
	s_waitcnt lgkmcnt(0)
	v_mfma_f32_16x16x32_bf16 v[72:75], v[72:75], v[8:11], 0
	v_and_b32_e32 v85, 0x7fffffff, v85
	v_and_b32_e32 v84, 0x7fffffff, v84
	v_pk_add_f32 v[58:59], v[58:59], v[84:85] neg_lo:[0,1] neg_hi:[0,1]
	v_pk_add_f32 v[54:55], v[54:55], v[84:85] neg_lo:[0,1] neg_hi:[0,1]
	v_sub_u32_e32 v84, 32, v86
	v_sub_u32_e32 v85, 33, v86
	v_cvt_f32_i32_e32 v85, v85
	v_cvt_f32_i32_e32 v84, v84
	v_max_f32_e32 v88, v52, v56
	v_max_f32_e32 v89, v53, v57
	v_max3_f32 v87, v87, v88, v89
	v_pk_mul_f32 v[84:85], v[148:149], v[84:85]
	v_max_f32_e32 v88, v54, v58
	v_and_b32_e32 v85, 0x7fffffff, v85
	v_and_b32_e32 v84, 0x7fffffff, v84
	v_pk_add_f32 v[64:65], v[64:65], v[84:85] neg_lo:[0,1] neg_hi:[0,1]
	v_pk_add_f32 v[60:61], v[60:61], v[84:85] neg_lo:[0,1] neg_hi:[0,1]
	v_sub_u32_e32 v84, 34, v86
	v_sub_u32_e32 v85, 35, v86
	v_cvt_f32_i32_e32 v85, v85
	v_cvt_f32_i32_e32 v84, v84
	v_max_f32_e32 v89, v55, v59
	v_max3_f32 v87, v87, v88, v89
	v_max_f32_e32 v88, v60, v64
	v_pk_mul_f32 v[84:85], v[148:149], v[84:85]
	v_max_f32_e32 v89, v61, v65
	v_and_b32_e32 v85, 0x7fffffff, v85
	v_and_b32_e32 v84, 0x7fffffff, v84
	v_pk_add_f32 v[66:67], v[66:67], v[84:85] neg_lo:[0,1] neg_hi:[0,1]
	v_pk_add_f32 v[62:63], v[62:63], v[84:85] neg_lo:[0,1] neg_hi:[0,1]
	v_sub_u32_e32 v84, 48, v86
	v_sub_u32_e32 v85, 49, v86
	v_cvt_f32_i32_e32 v85, v85
	v_cvt_f32_i32_e32 v84, v84
	v_max3_f32 v87, v87, v88, v89
	v_max_f32_e32 v88, v62, v66
	v_max_f32_e32 v89, v63, v67
	v_pk_mul_f32 v[84:85], v[148:149], v[84:85]
	v_max3_f32 v87, v87, v88, v89
	v_and_b32_e32 v85, 0x7fffffff, v85
	v_and_b32_e32 v84, 0x7fffffff, v84
	v_pk_add_f32 v[72:73], v[72:73], v[84:85] neg_lo:[0,1] neg_hi:[0,1]
	v_pk_add_f32 v[68:69], v[68:69], v[84:85] neg_lo:[0,1] neg_hi:[0,1]
	v_sub_u32_e32 v84, 50, v86
	v_sub_u32_e32 v85, 51, v86
	v_cvt_f32_i32_e32 v85, v85
	v_cvt_f32_i32_e32 v84, v84
	v_max_f32_e32 v86, v68, v72
	v_max_f32_e32 v88, v69, v73
	v_max3_f32 v86, v87, v86, v88
	v_pk_mul_f32 v[84:85], v[148:149], v[84:85]
	s_nop 0
	v_and_b32_e32 v85, 0x7fffffff, v85
	v_and_b32_e32 v84, 0x7fffffff, v84
	v_pk_add_f32 v[74:75], v[74:75], v[84:85] neg_lo:[0,1] neg_hi:[0,1]
	v_pk_add_f32 v[70:71], v[70:71], v[84:85] neg_lo:[0,1] neg_hi:[0,1]
	s_nop 0
	v_max_f32_e32 v84, v70, v74
	v_max_f32_e32 v85, v71, v75
	v_max3_f32 v84, v86, v84, v85
	v_and_b32_e32 v86, 64, v198
	v_mov_b32_e32 v85, v84
	v_mov_b32_e32 v255, v84
	s_nop 1
	v_permlane16_swap_b32_e32 v85, v255
	s_waitcnt lgkmcnt(0)
	v_max_f32_e32 v84, v85, v255
	v_mov_b32_e32 v85, v84
	v_mov_b32_e32 v255, v84
	s_nop 1
	v_permlane32_swap_b32_e32 v85, v255
	s_waitcnt lgkmcnt(0)
; DI void at_exp(f32x4 (&s1)[4], f32x4 (&s2)[4], float& ps1, float& ps2) {
;     f32x4 a1 = (f32x4){0.f, 0.f, 0.f, 0.f}, a2 = a1;
; #pragma unroll
;     for (int k4 = 0; k4 < 4; ++k4) {
; #pragma unroll
;         for (int j = 0; j < 4; ++j) { s1[k4][j] = fast_exp2(s1[k4][j]); s2[k4][j] = fast_exp2(s2[k4][j]); }
;         a1 = a1 + s1[k4]; a2 = a2 + s2[k4]; }
;     ps1 = (a1[0] + a1[1]) + (a1[2] + a1[3]); ps2 = (a2[0] + a2[1]) + (a2[2] + a2[3]);
; }
; DI void at_pv(AtState& S, const f32x4 (&s1)[4], const f32x4 (&s2)[4], float alpha, float ps1, float ps2, const LAS unsigned char* buf, int hh, int fq, int tq, int tp) {
;     S.l1 = S.l1 * alpha + ps1; S.l2 = S.l2 * alpha + ps2;
; #pragma unroll
;     for (int dt = 0; dt < 4; ++dt) { S.O1[dt] = S.O1[dt] * alpha; S.O2[dt] = S.O2[dt] * alpha; }
;     bf16x8 p1[2], p2[2];
; #pragma unroll
;     for (int s = 0; s < 2; ++s) { p1[s] = packp(s1[2 * s], s1[2 * s + 1]); p2[s] = packp(s2[2 * s], s2[2 * s + 1]); }
; #pragma unroll
;     for (int dh = 0; dh < 2; ++dh) {
;         bf16x8 vt[2][2];
; #pragma unroll
;         for (int d2 = 0; d2 < 2; ++d2)
; #pragma unroll
;             for (int s = 0; s < 2; ++s) { const int dt = 2 * dh + d2; const LAS unsigned char* vr = buf + AT_V + (32 * s + 4 * fq + tq) * 288 + (hh * 64 + 16 * dt + 4 * tp) * 2; vt[d2][s] = cat44(tr4(vr), tr4(vr + 16 * 288)); }
;         __builtin_amdgcn_s_setprio(1);
; #pragma unroll
;         for (int s = 0; s < 2; ++s)
; #pragma unroll
; template <int VAR>
; DI void attn_tile(AtState& S, const LAS unsigned char* buf, const bf16x8 q1, const bf16x8 q2, int kt, bool diag, int qpos0, int qpos_l, float slope2, float adv, float decay, int hh, int fr, int fq) {
;     ...
;         mx = fmaxf(mx, __shfl_xor(mx, 16)); mx = fmaxf(mx, __shfl_xor(mx, 32));
;         const float nref = fmaxf(S.ref, mx);
;         const float alpha = fast_exp2(S.ref - nref); S.ref = nref;
; #pragma unroll
;         for (int k4 = 0; k4 < 4; ++k4) { s1[k4] = s1[k4] - nref; s2[k4] = s2[k4] - nref; }
;         if (kt == 0) { const float c0 = -slope2 * (float)qpos0 - S.ref;
; #pragma unroll
;             for (int k4 = 0; k4 < 4; ++k4)
; #pragma unroll
;                 for (int j = 0; j < 4; ++j) S.cinit[k4][j] = slope2 * (float)(16 * k4 + j - ql) + c0; }
;         at_exp(s1, s2, ps1, ps2);
;         at_pv(S, s1, s2, alpha, ps1, ps2, buf, hh, fq, tq, tp);
	v_max3_f32 v214, v3, v255, v85
	v_sub_f32_e32 v47, v47, v214
	v_sub_f32_e32 v46, v46, v214
	v_sub_f32_e32 v45, v45, v214
	v_sub_f32_e32 v44, v44, v214
	v_sub_f32_e32 v51, v51, v214
	v_sub_f32_e32 v50, v50, v214
	v_sub_f32_e32 v49, v49, v214
	v_sub_f32_e32 v48, v48, v214
	v_sub_f32_e32 v55, v55, v214
	v_sub_f32_e32 v54, v54, v214
	v_sub_f32_e32 v53, v53, v214
	v_sub_f32_e32 v52, v52, v214
	v_sub_f32_e32 v59, v59, v214
	v_sub_f32_e32 v58, v58, v214
	v_sub_f32_e32 v57, v57, v214
	v_sub_f32_e32 v56, v56, v214
	v_sub_f32_e32 v84, v63, v214
	v_sub_f32_e32 v85, v62, v214
	v_sub_f32_e32 v87, v67, v214
	v_sub_f32_e32 v88, v66, v214
	v_sub_f32_e32 v89, v65, v214
	v_sub_f32_e32 v90, v64, v214
	v_sub_f32_e32 v93, v69, v214
	v_sub_f32_e32 v94, v68, v214
	v_exp_f32_e32 v62, v44
	v_exp_f32_e32 v64, v48
	v_exp_f32_e32 v63, v45
	v_exp_f32_e32 v65, v49
	v_exp_f32_e32 v66, v46
	v_exp_f32_e32 v67, v47
	v_exp_f32_e32 v68, v50
	v_exp_f32_e32 v69, v51
	v_sub_f32_e32 v61, v61, v214
	v_sub_f32_e32 v86, v60, v214
	v_sub_f32_e32 v91, v71, v214
	v_sub_f32_e32 v92, v70, v214
	v_sub_f32_e32 v95, v75, v214
	v_sub_f32_e32 v100, v74, v214
	v_sub_f32_e32 v101, v73, v214
	v_sub_f32_e32 v102, v72, v214
	v_exp_f32_e32 v70, v52
	v_exp_f32_e32 v72, v56
	v_exp_f32_e32 v71, v53
	v_exp_f32_e32 v74, v54
	v_exp_f32_e32 v75, v55
	v_exp_f32_e32 v162, v58
	v_exp_f32_e32 v163, v59
	v_exp_f32_e32 v73, v57
	v_exp_f32_e32 v164, v86
	v_exp_f32_e32 v166, v90
	v_exp_f32_e32 v165, v61
	v_exp_f32_e32 v167, v89
	v_exp_f32_e32 v168, v85
	v_exp_f32_e32 v169, v84
	v_exp_f32_e32 v170, v88
	v_exp_f32_e32 v171, v87
	v_exp_f32_e32 v172, v94
	v_exp_f32_e32 v174, v102
	v_exp_f32_e32 v173, v93
	v_exp_f32_e32 v176, v92
	v_exp_f32_e32 v177, v91
	v_exp_f32_e32 v178, v100
	v_exp_f32_e32 v179, v95
	v_exp_f32_e32 v175, v101
	v_pk_add_f32 v[44:45], v[62:63], 0 op_sel_hi:[1,0]
	v_pk_add_f32 v[46:47], v[66:67], 0 op_sel_hi:[1,0]
	v_pk_add_f32 v[48:49], v[64:65], 0 op_sel_hi:[1,0]
	v_pk_add_f32 v[50:51], v[68:69], 0 op_sel_hi:[1,0]
	v_pk_add_f32 v[46:47], v[74:75], v[46:47]
	v_pk_add_f32 v[44:45], v[70:71], v[44:45]
	v_pk_add_f32 v[50:51], v[162:163], v[50:51]
	v_pk_add_f32 v[48:49], v[72:73], v[48:49]
	v_sub_f32_e32 v3, v3, v214
	v_pk_add_f32 v[44:45], v[164:165], v[44:45]
	v_pk_add_f32 v[46:47], v[168:169], v[46:47]
	v_pk_add_f32 v[48:49], v[166:167], v[48:49]
	v_pk_add_f32 v[50:51], v[170:171], v[50:51]
	v_exp_f32_e32 v60, v3
	v_pk_add_f32 v[46:47], v[176:177], v[46:47]
	v_pk_add_f32 v[44:45], v[172:173], v[44:45]
	v_pk_add_f32 v[50:51], v[178:179], v[50:51]
	v_pk_add_f32 v[48:49], v[174:175], v[48:49]
	v_mov_b32_e32 v53, v44
	v_mov_b32_e32 v52, v48
	v_mov_b32_e32 v44, v49
	v_mov_b32_e32 v48, v50
	v_mov_b32_e32 v49, v46
	v_mov_b32_e32 v46, v51
	v_pk_add_f32 v[44:45], v[52:53], v[44:45]
	v_pk_add_f32 v[46:47], v[48:49], v[46:47]
	v_pk_mul_f32 v[50:51], v[118:119], v[60:61] op_sel_hi:[1,0]
	v_pk_add_f32 v[44:45], v[44:45], v[46:47]
	v_pk_mul_f32 v[46:47], v[122:123], v[60:61] op_sel_hi:[1,0]
	v_pk_fma_f32 v[156:157], v[158:159], v[60:61], v[44:45] op_sel_hi:[1,0,1]
	v_pk_mul_f32 v[44:45], v[120:121], v[60:61] op_sel_hi:[1,0]
	v_pk_mul_f32 v[48:49], v[116:117], v[60:61] op_sel_hi:[1,0]
	v_pk_mul_f32 v[54:55], v[114:115], v[60:61] op_sel_hi:[1,0]
	v_pk_mul_f32 v[52:53], v[112:113], v[60:61] op_sel_hi:[1,0]
	v_pk_mul_f32 v[58:59], v[110:111], v[60:61] op_sel_hi:[1,0]
	v_pk_mul_f32 v[56:57], v[108:109], v[60:61] op_sel_hi:[1,0]
	v_pk_mul_f32 v[86:87], v[138:139], v[60:61] op_sel_hi:[1,0]
	v_pk_mul_f32 v[84:85], v[136:137], v[60:61] op_sel_hi:[1,0]
	v_pk_mul_f32 v[90:91], v[134:135], v[60:61] op_sel_hi:[1,0]
	v_pk_mul_f32 v[88:89], v[132:133], v[60:61] op_sel_hi:[1,0]
	v_pk_mul_f32 v[94:95], v[130:131], v[60:61] op_sel_hi:[1,0]
	v_pk_mul_f32 v[92:93], v[128:129], v[60:61] op_sel_hi:[1,0]
	v_pk_mul_f32 v[102:103], v[126:127], v[60:61] op_sel_hi:[1,0]
	v_pk_mul_f32 v[100:101], v[124:125], v[60:61] op_sel_hi:[1,0]
	v_cvt_pk_bf16_f32 v108, v62, v63
	v_cvt_pk_bf16_f32 v109, v66, v67
	v_cvt_pk_bf16_f32 v110, v70, v71
	v_cvt_pk_bf16_f32 v112, v64, v65
	v_cvt_pk_bf16_f32 v113, v68, v69
	ds_read_b64_tr_b16 v[60:61], v208 offset:53248
	ds_read_b64_tr_b16 v[64:65], v208 offset:53280
	ds_read_b64_tr_b16 v[62:63], v208 offset:57856
	ds_read_b64_tr_b16 v[66:67], v208 offset:57888
	ds_read_b64_tr_b16 v[68:69], v208 offset:62464
	ds_read_b64_tr_b16 v[70:71], v209 offset:4608
	ds_read_b64_tr_b16 v[122:123], v210 offset:4608
	ds_read_b64_tr_b16 v[120:121], v208 offset:62496
	v_cvt_pk_bf16_f32 v111, v74, v75
	v_cvt_pk_bf16_f32 v114, v72, v73
	v_cvt_pk_bf16_f32 v115, v162, v163
	v_cvt_pk_bf16_f32 v116, v164, v165
	v_cvt_pk_bf16_f32 v117, v168, v169
	v_cvt_pk_bf16_f32 v118, v172, v173
	v_cvt_pk_bf16_f32 v119, v176, v177
	v_cvt_pk_bf16_f32 v124, v166, v167
	v_cvt_pk_bf16_f32 v125, v170, v171
	v_cvt_pk_bf16_f32 v126, v174, v175
	v_cvt_pk_bf16_f32 v127, v178, v179
	s_setprio 1
	s_waitcnt lgkmcnt(5)
	v_mfma_f32_16x16x32_bf16 v[44:47], v[60:63], v[108:111], v[44:47]
	v_mfma_f32_16x16x32_bf16 v[48:51], v[60:63], v[112:115], v[48:51]
	s_waitcnt lgkmcnt(4)
	v_mfma_f32_16x16x32_bf16 v[52:55], v[64:67], v[108:111], v[52:55]
	v_mfma_f32_16x16x32_bf16 v[56:59], v[64:67], v[112:115], v[56:59]
	s_waitcnt lgkmcnt(2)
	v_mfma_f32_16x16x32_bf16 v[64:67], v[68:71], v[116:119], v[44:47]
	v_mfma_f32_16x16x32_bf16 v[72:75], v[68:71], v[124:127], v[48:51]
	s_waitcnt lgkmcnt(0)
	v_mfma_f32_16x16x32_bf16 v[60:63], v[120:123], v[116:119], v[52:55]
	v_mfma_f32_16x16x32_bf16 v[68:71], v[120:123], v[124:127], v[56:59]
	s_setprio 0
	ds_read_b64_tr_b16 v[44:45], v208 offset:53312
	ds_read_b64_tr_b16 v[48:49], v208 offset:53344
	ds_read_b64_tr_b16 v[46:47], v208 offset:57920
	ds_read_b64_tr_b16 v[50:51], v208 offset:57952
	ds_read_b64_tr_b16 v[52:53], v208 offset:62528
	ds_read_b64_tr_b16 v[54:55], v211 offset:4608
	ds_read_b64_tr_b16 v[58:59], v212 offset:4608
	ds_read_b64_tr_b16 v[56:57], v208 offset:62560
	s_setprio 1
	s_waitcnt lgkmcnt(5)
	v_mfma_f32_16x16x32_bf16 v[84:87], v[44:47], v[108:111], v[84:87]
	v_mfma_f32_16x16x32_bf16 v[44:47], v[44:47], v[112:115], v[88:91]
	s_waitcnt lgkmcnt(4)
	v_mfma_f32_16x16x32_bf16 v[92:95], v[48:51], v[108:111], v[92:95]
	v_mfma_f32_16x16x32_bf16 v[48:51], v[48:51], v[112:115], v[100:103]
	s_waitcnt lgkmcnt(2)
	v_mfma_f32_16x16x32_bf16 v[88:91], v[52:55], v[116:119], v[84:87]
	v_mfma_f32_16x16x32_bf16 v[100:103], v[52:55], v[124:127], v[44:47]
	s_waitcnt lgkmcnt(0)
	v_mfma_f32_16x16x32_bf16 v[84:87], v[56:59], v[116:119], v[92:95]
	v_mfma_f32_16x16x32_bf16 v[92:95], v[56:59], v[124:127], v[48:51]
	s_setprio 0
	v_mov_b64_e32 v[52:53], v[104:105]
	s_nop 0
	v_mov_b64_e32 v[48:49], v[96:97]
	v_mov_b64_e32 v[44:45], v[76:77]
	v_mov_b64_e32 v[56:57], v[80:81]
	v_mov_b64_e32 v[54:55], v[106:107]
	v_mov_b64_e32 v[50:51], v[98:99]
	v_mov_b64_e32 v[46:47], v[78:79]
	v_mov_b64_e32 v[58:59], v[82:83]

; template <int VAR>
; DI void attn_tile(AtState& S, const LAS unsigned char* buf, const bf16x8 q1, const bf16x8 q2, int kt, bool diag, int qpos0, int qpos_l, float slope2, float adv, float decay, int hh, int fr, int fq) {
;     ...
;         asm volatile("; attention: fast tile" ::: "memory");
;         at_qk(s1, s2, buf, q1, q2, S.cinit, hh, fr, fq);
;         S.ref += adv;
;         at_exp(s1, s2, ps1, ps2);
;         if (__any(!(ps1 + ps2 < 0x1p60f))) {
;             asm volatile("; attention: bump" ::: "memory");
;             at_qk(s1, s2, buf, q1, q2, S.cinit, hh, fr, fq);
;             float lm = -1e30f;
; #pragma unroll
;             for (int k4 = 0; k4 < 4; ++k4)
; #pragma unroll
;                 for (int j = 0; j < 4; ++j) lm = fmaxf(lm, fmaxf(s1[k4][j], s2[k4][j]));
;             lm = fmaxf(lm, __shfl_xor(lm, 16)); lm = fmaxf(lm, __shfl_xor(lm, 32));
; template <int VAR>
; DI void attn_segment(const Args& a, const Frame& F, int l, int qrow0, int qpos0, int hp, int ntile, int nf32, const float* ck, const float* cv, int prow0) {
;     ...
;         for (int kt = 0; kt < ntile; ++kt) {
;             const bool more = kt + 1 < ntile; bool nf32s = false;
;             if (more) { const void *kp, *vp; size_t rs; at_src(kt + 1, nf32, ck, cv, P, prow0, hp, kp, vp, rs, nf32s); at_issue(raw, kp, vp, rs, nf32s, tid); }
;             attn_tile<VAR>(S, F.lds + (kt & 1) * AT_BUF, q1, q2, kt, !more, qpos0, qpos_l, slope2, adv, decay, hh, fr, fq);
.LBB0_1405:
	s_bitcmp1_b32 s40, 0
	s_cselect_b32 s26, 0x8c00, 0
	s_add_i32 s28, s41, s26
	s_sub_i32 s27, s40, 32
	v_add_u32_e32 v3, s28, v206
	s_cmp_gt_u32 s27, 0xffffffe0
	s_mov_b64 s[26:27], -1
	v_add_u32_e32 v3, v3, v207
	s_cbranch_scc0 .LBB0_1410
	ds_read_b128 v[62:65], v3
	ds_read_b128 v[66:69], v3 offset:64
	ds_read_b128 v[70:73], v3 offset:4352
	ds_read_b128 v[74:77], v3 offset:4416
	ds_read_b128 v[78:81], v3 offset:8704
	ds_read_b128 v[82:85], v3 offset:8768
	ds_read_b128 v[86:89], v3 offset:13056
	ds_read_b128 v[90:93], v3 offset:13120
	s_waitcnt lgkmcnt(7)
	v_mfma_f32_16x16x32_bf16 v[62:65], v[62:65], v[38:41], v[46:49]
	v_add_f32_e32 v213, v204, v212
	s_waitcnt lgkmcnt(6)
	v_mfma_f32_16x16x32_bf16 v[66:69], v[66:69], v[42:45], v[46:49]
	s_waitcnt lgkmcnt(5)
	v_mfma_f32_16x16x32_bf16 v[70:73], v[70:73], v[38:41], v[50:53]
	s_nop 2
	v_exp_f32_e32 v164, v62
	v_exp_f32_e32 v165, v63
	v_exp_f32_e32 v168, v64
	s_waitcnt lgkmcnt(4)
	v_mfma_f32_16x16x32_bf16 v[74:77], v[74:77], v[42:45], v[50:53]
	v_exp_f32_e32 v169, v65
	v_exp_f32_e32 v162, v66
	v_exp_f32_e32 v163, v67
	s_waitcnt lgkmcnt(3)
	v_mfma_f32_16x16x32_bf16 v[78:81], v[78:81], v[38:41], v[54:57]
	v_exp_f32_e32 v166, v68
	v_exp_f32_e32 v167, v69
	v_exp_f32_e32 v172, v70
	s_waitcnt lgkmcnt(2)
	v_mfma_f32_16x16x32_bf16 v[62:65], v[82:85], v[42:45], v[54:57]
	v_exp_f32_e32 v170, v74
	v_exp_f32_e32 v173, v71
	v_exp_f32_e32 v176, v72
	s_waitcnt lgkmcnt(1)
	v_mfma_f32_16x16x32_bf16 v[66:69], v[86:89], v[38:41], v[58:61]
	v_exp_f32_e32 v177, v73
	v_exp_f32_e32 v174, v76
	v_exp_f32_e32 v175, v77
	s_waitcnt lgkmcnt(0)
	v_mfma_f32_16x16x32_bf16 v[82:85], v[90:93], v[42:45], v[58:61]
	v_exp_f32_e32 v171, v75
	v_exp_f32_e32 v180, v78
	v_exp_f32_e32 v178, v62
	v_exp_f32_e32 v181, v79
	v_exp_f32_e32 v179, v63
	v_exp_f32_e32 v184, v80
	v_exp_f32_e32 v185, v81
	v_exp_f32_e32 v182, v64
	v_exp_f32_e32 v183, v65
	v_exp_f32_e32 v188, v66
	v_exp_f32_e32 v186, v82
	v_exp_f32_e32 v189, v67
	v_exp_f32_e32 v192, v68
	v_exp_f32_e32 v193, v69
	v_exp_f32_e32 v190, v84
	v_exp_f32_e32 v191, v85
	v_exp_f32_e32 v187, v83
	v_pk_add_f32 v[94:95], v[164:165], 0 op_sel_hi:[1,0]
	v_pk_add_f32 v[96:97], v[168:169], 0 op_sel_hi:[1,0]
	v_pk_add_f32 v[86:87], v[162:163], 0 op_sel_hi:[1,0]
	v_pk_add_f32 v[88:89], v[166:167], 0 op_sel_hi:[1,0]
	v_pk_add_f32 v[70:71], v[96:97], v[176:177]
	v_pk_add_f32 v[72:73], v[94:95], v[172:173]
	v_pk_add_f32 v[74:75], v[88:89], v[174:175]
	v_pk_add_f32 v[76:77], v[86:87], v[170:171]
	v_pk_add_f32 v[62:63], v[72:73], v[180:181]
	v_pk_add_f32 v[64:65], v[70:71], v[184:185]
	v_pk_add_f32 v[70:71], v[76:77], v[178:179]
	v_pk_add_f32 v[72:73], v[74:75], v[182:183]
	v_pk_add_f32 v[64:65], v[64:65], v[192:193]
	v_pk_add_f32 v[62:63], v[62:63], v[188:189]
	v_pk_add_f32 v[66:67], v[72:73], v[190:191]
	v_pk_add_f32 v[68:69], v[70:71], v[186:187]
	v_mov_b32_e32 v71, v62
	v_mov_b32_e32 v70, v68
	v_mov_b32_e32 v62, v69
	v_mov_b32_e32 v68, v66
	v_mov_b32_e32 v69, v64
	v_mov_b32_e32 v64, v67
	v_pk_add_f32 v[62:63], v[70:71], v[62:63]
	v_pk_add_f32 v[64:65], v[68:69], v[64:65]
	s_nop 0
	v_pk_add_f32 v[194:195], v[62:63], v[64:65]
	s_nop 0
	v_add_f32_e32 v62, v195, v194
	v_cmp_ngt_f32_e32 vcc, s65, v62
	s_cbranch_vccz .LBB0_1416
	ds_read_b128 v[62:65], v3
	ds_read_b128 v[66:69], v3 offset:64
	ds_read_b128 v[70:73], v3 offset:4352
	ds_read_b128 v[74:77], v3 offset:4416
	ds_read_b128 v[78:81], v3 offset:8704
	ds_read_b128 v[82:85], v3 offset:8768
	ds_read_b128 v[86:89], v3 offset:13056
	ds_read_b128 v[90:93], v3 offset:13120
	v_add3_u32 v246, s28, v208, v209
	s_waitcnt lgkmcnt(7)
	v_mfma_f32_16x16x32_bf16 v[62:65], v[62:65], v[38:41], v[46:49]
	s_waitcnt lgkmcnt(6)
	v_mfma_f32_16x16x32_bf16 v[66:69], v[66:69], v[42:45], v[46:49]
	s_waitcnt lgkmcnt(5)
	v_mfma_f32_16x16x32_bf16 v[70:73], v[70:73], v[38:41], v[50:53]
	s_nop 3
	v_max_f32_e32 v95, v62, v62
	s_nop 0
	v_max_f32_e32 v94, v66, v66
	v_max_f32_e32 v94, v95, v94
	v_max_f32_e32 v95, v67, v67
	v_max_f32_e32 v96, v63, v63
	s_waitcnt lgkmcnt(4)
	v_mfma_f32_16x16x32_bf16 v[74:77], v[74:77], v[42:45], v[50:53]
	v_max_f32_e32 v95, v96, v95
	v_max3_f32 v94, v94, s60, v95
	v_max_f32_e32 v95, v68, v68
	v_max_f32_e32 v96, v64, v64
	v_max_f32_e32 v95, v96, v95
	v_max_f32_e32 v96, v69, v69
	v_max_f32_e32 v97, v65, v65
	v_max_f32_e32 v96, v97, v96
	v_max3_f32 v94, v94, v95, v96
	v_max_f32_e32 v95, v74, v74
	v_max_f32_e32 v96, v70, v70
	v_max_f32_e32 v95, v96, v95
	v_max_f32_e32 v96, v75, v75
	v_max_f32_e32 v97, v71, v71
	s_waitcnt lgkmcnt(3)
	v_mfma_f32_16x16x32_bf16 v[78:81], v[78:81], v[38:41], v[54:57]
	v_max_f32_e32 v96, v97, v96
	v_max3_f32 v94, v94, v95, v96
	v_max_f32_e32 v95, v76, v76
	s_waitcnt lgkmcnt(2)
	v_mfma_f32_16x16x32_bf16 v[82:85], v[82:85], v[42:45], v[54:57]
	v_max_f32_e32 v96, v72, v72
	v_max_f32_e32 v95, v96, v95
	v_max_f32_e32 v96, v77, v77
	v_max_f32_e32 v97, v73, v73
	v_max_f32_e32 v96, v97, v96
	v_max3_f32 v94, v94, v95, v96
	s_nop 1
	v_max_f32_e32 v95, v82, v82
	v_max_f32_e32 v96, v78, v78
	v_max_f32_e32 v95, v96, v95
	v_max_f32_e32 v96, v83, v83
	v_max_f32_e32 v97, v79, v79
	s_waitcnt lgkmcnt(1)
	v_mfma_f32_16x16x32_bf16 v[86:89], v[86:89], v[38:41], v[58:61]
	v_max_f32_e32 v96, v97, v96
	v_max3_f32 v94, v94, v95, v96
	v_max_f32_e32 v95, v84, v84
	s_waitcnt lgkmcnt(0)
; DI void at_exp(f32x4 (&s1)[4], f32x4 (&s2)[4], float& ps1, float& ps2) {
;     f32x4 a1 = (f32x4){0.f, 0.f, 0.f, 0.f}, a2 = a1;
; #pragma unroll
;     for (int k4 = 0; k4 < 4; ++k4) {
; #pragma unroll
;         for (int j = 0; j < 4; ++j) { s1[k4][j] = fast_exp2(s1[k4][j]); s2[k4][j] = fast_exp2(s2[k4][j]); }
;         a1 = a1 + s1[k4]; a2 = a2 + s2[k4]; }
;     ps1 = (a1[0] + a1[1]) + (a1[2] + a1[3]); ps2 = (a2[0] + a2[1]) + (a2[2] + a2[3]);
; }
; DI void at_pv(AtState& S, const f32x4 (&s1)[4], const f32x4 (&s2)[4], float alpha, float ps1, float ps2, const LAS unsigned char* buf, int hh, int fq, int tq, int tp) {
;     S.l1 = S.l1 * alpha + ps1; S.l2 = S.l2 * alpha + ps2;
; #pragma unroll
;     for (int dt = 0; dt < 4; ++dt) { S.O1[dt] = S.O1[dt] * alpha; S.O2[dt] = S.O2[dt] * alpha; }
;     bf16x8 p1[2], p2[2];
; #pragma unroll
;     for (int s = 0; s < 2; ++s) { p1[s] = packp(s1[2 * s], s1[2 * s + 1]); p2[s] = packp(s2[2 * s], s2[2 * s + 1]); }
; #pragma unroll
;     for (int dh = 0; dh < 2; ++dh) {
;         bf16x8 vt[2][2];
; #pragma unroll
;         for (int d2 = 0; d2 < 2; ++d2)
; #pragma unroll
;             for (int s = 0; s < 2; ++s) { const int dt = 2 * dh + d2; const LAS unsigned char* vr = buf + AT_V + (32 * s + 4 * fq + tq) * 288 + (hh * 64 + 16 * dt + 4 * tp) * 2; vt[d2][s] = cat44(tr4(vr), tr4(vr + 16 * 288)); }
;         __builtin_amdgcn_s_setprio(1);
; #pragma unroll
; template <int VAR>
; DI void attn_tile(AtState& S, const LAS unsigned char* buf, const bf16x8 q1, const bf16x8 q2, int kt, bool diag, int qpos0, int qpos_l, float slope2, float adv, float decay, int hh, int fr, int fq) {
;     ...
;             at_qk(s1, s2, buf, q1, q2, S.cinit, hh, fr, fq);
;             float lm = -1e30f;
; #pragma unroll
;             for (int k4 = 0; k4 < 4; ++k4)
; #pragma unroll
;                 for (int j = 0; j < 4; ++j) lm = fmaxf(lm, fmaxf(s1[k4][j], s2[k4][j]));
;             lm = fmaxf(lm, __shfl_xor(lm, 16)); lm = fmaxf(lm, __shfl_xor(lm, 32));
;             const float bump = fmaxf(lm, 0.f);
;             const float alpha = decay * fast_exp2(-bump); S.ref += bump;
; #pragma unroll
;             for (int k4 = 0; k4 < 4; ++k4) { s1[k4] = s1[k4] - bump; s2[k4] = s2[k4] - bump; S.cinit[k4] = S.cinit[k4] - bump; }
;             at_exp(s1, s2, ps1, ps2);
;             at_pv(S, s1, s2, alpha, ps1, ps2, buf, hh, fq, tq, tp);
	v_mfma_f32_16x16x32_bf16 v[90:93], v[90:93], v[42:45], v[58:61]
	v_max_f32_e32 v96, v80, v80
	v_max_f32_e32 v95, v96, v95
	v_max_f32_e32 v96, v85, v85
	v_max_f32_e32 v97, v81, v81
	v_max_f32_e32 v96, v97, v96
	v_max3_f32 v94, v94, v95, v96
	s_nop 1
	v_max_f32_e32 v95, v90, v90
	v_max_f32_e32 v96, v86, v86
	v_max_f32_e32 v95, v96, v95
	v_max_f32_e32 v96, v91, v91
	v_max_f32_e32 v97, v87, v87
	v_max_f32_e32 v96, v97, v96
	v_max3_f32 v94, v94, v95, v96
	v_max_f32_e32 v95, v92, v92
	v_max_f32_e32 v96, v88, v88
	v_max_f32_e32 v95, v96, v95
	v_max_f32_e32 v96, v93, v93
	v_max_f32_e32 v97, v89, v89
	v_max_f32_e32 v96, v97, v96
	v_max3_f32 v94, v94, v95, v96
	v_and_b32_e32 v96, 64, v198
	v_mov_b32_e32 v95, v94
	v_mov_b32_e32 v255, v94
	s_nop 1
	v_permlane16_swap_b32_e32 v95, v255
	s_waitcnt lgkmcnt(0)
	v_max_f32_e32 v94, v95, v255
	v_mov_b32_e32 v95, v94
	v_mov_b32_e32 v255, v94
	s_nop 1
	v_permlane32_swap_b32_e32 v95, v255
	s_waitcnt lgkmcnt(0)
	v_max3_f32 v94, v255, v95, 0
	v_sub_f32_e32 v96, v65, v94
	v_sub_f32_e32 v97, v64, v94
	v_sub_f32_e32 v98, v63, v94
	v_sub_f32_e32 v99, v62, v94
	v_sub_f32_e32 v69, v69, v94
	v_sub_f32_e32 v68, v68, v94
	v_sub_f32_e32 v67, v67, v94
	v_sub_f32_e32 v66, v66, v94
	v_sub_f32_e32 v100, v73, v94
	v_sub_f32_e32 v101, v72, v94
	v_sub_f32_e32 v102, v71, v94
	v_sub_f32_e32 v103, v70, v94
	v_sub_f32_e32 v104, v77, v94
	v_sub_f32_e32 v105, v76, v94
	v_sub_f32_e32 v107, v75, v94
	v_sub_f32_e32 v108, v74, v94
	v_exp_f32_e32 v214, v99
	v_exp_f32_e32 v218, v66
	v_exp_f32_e32 v215, v98
	v_exp_f32_e32 v219, v67
	v_exp_f32_e32 v216, v97
	v_exp_f32_e32 v220, v68
	v_exp_f32_e32 v217, v96
	v_exp_f32_e32 v221, v69
	v_sub_f32_e32 v109, v81, v94
	v_sub_f32_e32 v158, v80, v94
	v_sub_f32_e32 v159, v79, v94
	v_sub_f32_e32 v230, v78, v94
	v_sub_f32_e32 v85, v85, v94
	v_sub_f32_e32 v84, v84, v94
	v_sub_f32_e32 v83, v83, v94
	v_sub_f32_e32 v82, v82, v94
	v_exp_f32_e32 v222, v103
	v_exp_f32_e32 v224, v108
	v_exp_f32_e32 v223, v102
	v_exp_f32_e32 v225, v107
	v_exp_f32_e32 v226, v101
	v_exp_f32_e32 v228, v105
	v_exp_f32_e32 v227, v100
	v_exp_f32_e32 v229, v104
	v_sub_f32_e32 v89, v89, v94
	v_sub_f32_e32 v88, v88, v94
	v_sub_f32_e32 v87, v87, v94
	v_sub_f32_e32 v86, v86, v94
	v_sub_f32_e32 v245, v93, v94
	v_sub_f32_e32 v243, v92, v94
	v_sub_f32_e32 v241, v91, v94
	v_sub_f32_e32 v239, v90, v94
	v_exp_f32_e32 v230, v230
	v_exp_f32_e32 v232, v82
	v_exp_f32_e32 v231, v159
	v_exp_f32_e32 v233, v83
	v_exp_f32_e32 v234, v158
	v_exp_f32_e32 v236, v84
	v_exp_f32_e32 v235, v109
	v_exp_f32_e32 v237, v85
	v_exp_f32_e32 v238, v86
	v_exp_f32_e32 v240, v239
	v_exp_f32_e32 v239, v87
	v_exp_f32_e32 v241, v241
	v_exp_f32_e32 v242, v88
	v_exp_f32_e32 v244, v243
	v_exp_f32_e32 v243, v89
	v_exp_f32_e32 v245, v245
	v_pk_add_f32 v[66:67], v[214:215], 0 op_sel_hi:[1,0]
	v_pk_add_f32 v[68:69], v[216:217], 0 op_sel_hi:[1,0]
	v_pk_add_f32 v[70:71], v[218:219], 0 op_sel_hi:[1,0]
	v_pk_add_f32 v[72:73], v[220:221], 0 op_sel_hi:[1,0]
	v_pk_add_f32 v[68:69], v[226:227], v[68:69]
	v_pk_add_f32 v[66:67], v[222:223], v[66:67]
	v_pk_add_f32 v[72:73], v[228:229], v[72:73]
	v_pk_add_f32 v[70:71], v[224:225], v[70:71]
	v_pk_add_f32 v[66:67], v[230:231], v[66:67]
	v_pk_add_f32 v[68:69], v[234:235], v[68:69]
	v_pk_add_f32 v[70:71], v[232:233], v[70:71]
	v_pk_add_f32 v[72:73], v[236:237], v[72:73]
	v_pk_add_f32 v[68:69], v[242:243], v[68:69]
	v_pk_add_f32 v[66:67], v[238:239], v[66:67]
	v_pk_add_f32 v[72:73], v[244:245], v[72:73]
	v_pk_add_f32 v[70:71], v[240:241], v[70:71]
	v_cvt_pk_bf16_f32 v214, v214, v215
	v_cvt_pk_bf16_f32 v215, v216, v217
	v_cvt_pk_bf16_f32 v216, v222, v223
	v_cvt_pk_bf16_f32 v217, v226, v227
	v_cvt_pk_bf16_f32 v218, v218, v219
	v_cvt_pk_bf16_f32 v219, v220, v221
	v_cvt_pk_bf16_f32 v220, v224, v225
	v_cvt_pk_bf16_f32 v221, v228, v229
	v_cvt_pk_bf16_f32 v222, v230, v231
	v_cvt_pk_bf16_f32 v223, v234, v235
	v_cvt_pk_bf16_f32 v224, v238, v239
	v_cvt_pk_bf16_f32 v225, v242, v243
	v_cvt_pk_bf16_f32 v226, v232, v233
	v_cvt_pk_bf16_f32 v227, v236, v237
	v_cvt_pk_bf16_f32 v228, v240, v241
	v_cvt_pk_bf16_f32 v229, v244, v245
	ds_read_b64_tr_b16 v[230:231], v246 offset:17408
	ds_read_b64_tr_b16 v[234:235], v246 offset:17440
	ds_read_b64_tr_b16 v[232:233], v246 offset:22016
	ds_read_b64_tr_b16 v[238:239], v246 offset:26624
	ds_read_b64_tr_b16 v[240:241], v246 offset:31232
	ds_read_b64_tr_b16 v[236:237], v246 offset:22048
	ds_read_b64_tr_b16 v[242:243], v246 offset:26656
	ds_read_b64_tr_b16 v[244:245], v246 offset:31264
	v_exp_f32_e64 v95, -v94
	v_mov_b32_e32 v82, v70
	v_mov_b32_e32 v83, v66
	v_mov_b32_e32 v66, v71
	v_mov_b32_e32 v70, v72
	v_mov_b32_e32 v71, v68
	v_mov_b32_e32 v68, v73
	v_pk_add_f32 v[66:67], v[82:83], v[66:67]
	v_pk_add_f32 v[68:69], v[70:71], v[68:69]
	v_mul_f32_e32 v106, v116, v95
	v_pk_add_f32 v[66:67], v[66:67], v[68:69]
	v_add_f32_e32 v117, v213, v94
	v_sub_f32_e32 v65, v49, v94
	v_sub_f32_e32 v64, v48, v94
	v_sub_f32_e32 v63, v47, v94
	v_sub_f32_e32 v62, v46, v94
	v_sub_f32_e32 v77, v53, v94
	v_sub_f32_e32 v76, v52, v94
	v_sub_f32_e32 v75, v51, v94
	v_sub_f32_e32 v74, v50, v94
	v_sub_f32_e32 v81, v57, v94
	v_sub_f32_e32 v80, v56, v94
	v_sub_f32_e32 v79, v55, v94
	v_sub_f32_e32 v78, v54, v94
	v_sub_f32_e32 v93, v61, v94
	v_sub_f32_e32 v92, v60, v94
	v_sub_f32_e32 v91, v59, v94
	v_sub_f32_e32 v90, v58, v94
	v_pk_fma_f32 v[158:159], v[156:157], v[106:107], v[66:67] op_sel_hi:[1,0,1]
	v_pk_mul_f32 v[68:69], v[154:155], v[106:107] op_sel_hi:[1,0]
	v_pk_mul_f32 v[66:67], v[152:153], v[106:107] op_sel_hi:[1,0]
	v_pk_mul_f32 v[72:73], v[150:151], v[106:107] op_sel_hi:[1,0]
	v_pk_mul_f32 v[70:71], v[148:149], v[106:107] op_sel_hi:[1,0]
	v_pk_mul_f32 v[84:85], v[146:147], v[106:107] op_sel_hi:[1,0]
	v_pk_mul_f32 v[82:83], v[144:145], v[106:107] op_sel_hi:[1,0]
	v_pk_mul_f32 v[88:89], v[138:139], v[106:107] op_sel_hi:[1,0]
	v_pk_mul_f32 v[86:87], v[136:137], v[106:107] op_sel_hi:[1,0]
	v_pk_mul_f32 v[96:97], v[134:135], v[106:107] op_sel_hi:[1,0]
	v_pk_mul_f32 v[94:95], v[132:133], v[106:107] op_sel_hi:[1,0]
	v_pk_mul_f32 v[100:101], v[130:131], v[106:107] op_sel_hi:[1,0]
	v_pk_mul_f32 v[98:99], v[128:129], v[106:107] op_sel_hi:[1,0]
	v_pk_mul_f32 v[104:105], v[126:127], v[106:107] op_sel_hi:[1,0]
	v_pk_mul_f32 v[102:103], v[124:125], v[106:107] op_sel_hi:[1,0]
	v_pk_mul_f32 v[108:109], v[4:5], v[106:107] op_sel_hi:[1,0]
	v_pk_mul_f32 v[106:107], v[122:123], v[106:107] op_sel_hi:[1,0]
	s_setprio 1
	s_waitcnt lgkmcnt(5)
; #define LAS __attribute__((address_space(3)))
; #define MFMA16(a, b, c) __builtin_amdgcn_mfma_f32_16x16x32_bf16((a), (b), (c), 0, 0, 0)
; DI u32x2 tr4(const LAS unsigned char* p) { return __builtin_bit_cast(u32x2, __builtin_amdgcn_ds_read_tr16_b64_v4i16((LAS v4i16_t*)p)); }
; DI void at_pv(AtState& S, const f32x4 (&s1)[4], const f32x4 (&s2)[4], float alpha, float ps1, float ps2, const LAS unsigned char* buf, int hh, int fq, int tq, int tp) {
;     ...
;     for (int dh = 0; dh < 2; ++dh) {
;         bf16x8 vt[2][2];
; #pragma unroll
;         for (int d2 = 0; d2 < 2; ++d2)
; #pragma unroll
;             for (int s = 0; s < 2; ++s) { const int dt = 2 * dh + d2; const LAS unsigned char* vr = buf + AT_V + (32 * s + 4 * fq + tq) * 288 + (hh * 64 + 16 * dt + 4 * tp) * 2; vt[d2][s] = cat44(tr4(vr), tr4(vr + 16 * 288)); }
;         __builtin_amdgcn_s_setprio(1);
; #pragma unroll
;         for (int s = 0; s < 2; ++s)
; #pragma unroll
;             for (int d2 = 0; d2 < 2; ++d2) { const int dt = 2 * dh + d2; S.O1[dt] = MFMA16(vt[d2][s], p1[s], S.O1[dt]); S.O2[dt] = MFMA16(vt[d2][s], p2[s], S.O2[dt]); }
;         __builtin_amdgcn_s_setprio(0);
;         __builtin_amdgcn_sched_barrier(0);
;     }
	v_mfma_f32_16x16x32_bf16 v[66:69], v[230:233], v[214:217], v[66:69]
	v_mfma_f32_16x16x32_bf16 v[70:73], v[230:233], v[218:221], v[70:73]
	s_waitcnt lgkmcnt(2)
	v_mfma_f32_16x16x32_bf16 v[82:85], v[234:237], v[214:217], v[82:85]
	v_mfma_f32_16x16x32_bf16 v[230:233], v[234:237], v[218:221], v[86:89]
	v_mfma_f32_16x16x32_bf16 v[66:69], v[238:241], v[222:225], v[66:69]
	v_mfma_f32_16x16x32_bf16 v[86:89], v[238:241], v[226:229], v[70:73]
	s_waitcnt lgkmcnt(0)
	v_mfma_f32_16x16x32_bf16 v[70:73], v[242:245], v[222:225], v[82:85]
	v_mfma_f32_16x16x32_bf16 v[82:85], v[242:245], v[226:229], v[230:233]
	s_setprio 0
	s_nop 1
	ds_read_b64_tr_b16 v[230:231], v246 offset:17472
	ds_read_b64_tr_b16 v[234:235], v246 offset:17504
	ds_read_b64_tr_b16 v[232:233], v246 offset:22080
	ds_read_b64_tr_b16 v[236:237], v246 offset:22112
	ds_read_b64_tr_b16 v[238:239], v246 offset:26688
	ds_read_b64_tr_b16 v[240:241], v246 offset:31296
	ds_read_b64_tr_b16 v[244:245], v246 offset:31328
	ds_read_b64_tr_b16 v[242:243], v246 offset:26720
	s_setprio 1
	s_waitcnt lgkmcnt(5)
	v_mfma_f32_16x16x32_bf16 v[94:97], v[230:233], v[214:217], v[94:97]
	v_mfma_f32_16x16x32_bf16 v[98:101], v[230:233], v[218:221], v[98:101]
	s_waitcnt lgkmcnt(4)
	v_mfma_f32_16x16x32_bf16 v[102:105], v[234:237], v[214:217], v[102:105]
	v_mfma_f32_16x16x32_bf16 v[214:217], v[234:237], v[218:221], v[106:109]
	s_waitcnt lgkmcnt(2)
	v_mfma_f32_16x16x32_bf16 v[94:97], v[238:241], v[222:225], v[94:97]
	v_mfma_f32_16x16x32_bf16 v[106:109], v[238:241], v[226:229], v[98:101]
	s_waitcnt lgkmcnt(0)
	v_mfma_f32_16x16x32_bf16 v[98:101], v[242:245], v[222:225], v[102:105]
	v_mfma_f32_16x16x32_bf16 v[102:105], v[242:245], v[226:229], v[214:217]
	s_setprio 0
	s_cbranch_execnz .LBB0_1409

; DI float fast_exp2(float x) { return __builtin_amdgcn_exp2f(x); }
; template <int VAR>
; DI void attn_tile(AtState& S, const LAS unsigned char* buf, const bf16x8 q1, const bf16x8 q2, int kt, bool diag, int qpos0, int qpos_l, float slope2, float adv, float decay, int hh, int fr, int fq) {
;     ...
;         asm volatile("; attention: exact tile" ::: "memory");
;         { f32x4 z[4];
; #pragma unroll
;           for (int k4 = 0; k4 < 4; ++k4) z[k4] = (f32x4){0.f, 0.f, 0.f, 0.f};
;           at_qk(s1, s2, buf, q1, q2, z, hh, fr, fq); }
;         int ql = qpos_l - 4 * fq; asm volatile("" : "+v"(ql));
;         const float dk = slope2 * (float)(qpos0 - kt * 64);
;         float mx = -1e30f;
; #pragma unroll
;         for (int k4 = 0; k4 < 4; ++k4)
; #pragma unroll
;             for (int j = 0; j < 4; ++j) { const float g = slope2 * (float)(16 * k4 + j - ql); const float bias = diag ? -fabsf(g) : g - dk;
;                 s1[k4][j] += bias; s2[k4][j] += bias; mx = fmaxf(mx, fmaxf(s1[k4][j], s2[k4][j])); }
;         mx = fmaxf(mx, __shfl_xor(mx, 16)); mx = fmaxf(mx, __shfl_xor(mx, 32));
;         const float nref = fmaxf(S.ref, mx);
;         const float alpha = fast_exp2(S.ref - nref); S.ref = nref;
; #pragma unroll
;         for (int k4 = 0; k4 < 4; ++k4) { s1[k4] = s1[k4] - nref; s2[k4] = s2[k4] - nref; }
;         if (kt == 0) { const float c0 = -slope2 * (float)qpos0 - S.ref;
; #pragma unroll
;             for (int k4 = 0; k4 < 4; ++k4)
; #pragma unroll
;                 for (int j = 0; j < 4; ++j) S.cinit[k4][j] = slope2 * (float)(16 * k4 + j - ql) + c0; }
.LBB0_1410:
	s_andn2_b64 vcc, exec, s[26:27]
	s_cbranch_vccnz .LBB0_1414
	ds_read_b128 v[62:65], v3
	ds_read_b128 v[66:69], v3 offset:13120
	v_mov_b32_e32 v109, v210
	v_cvt_f32_u32_e32 v117, s42
	s_cmp_lg_u32 s40, 0
	s_waitcnt lgkmcnt(1)
	v_mfma_f32_16x16x32_bf16 v[80:83], v[62:65], v[38:41], 0
	ds_read_b128 v[62:65], v3 offset:64
	s_waitcnt lgkmcnt(1)
	v_mfma_f32_16x16x32_bf16 v[66:69], v[66:69], v[42:45], 0
	s_waitcnt lgkmcnt(0)
	v_mfma_f32_16x16x32_bf16 v[84:87], v[62:65], v[42:45], 0
	ds_read_b128 v[62:65], v3 offset:4352
	s_waitcnt lgkmcnt(0)
	v_mfma_f32_16x16x32_bf16 v[98:101], v[62:65], v[38:41], 0
	ds_read_b128 v[62:65], v3 offset:4416
	s_waitcnt lgkmcnt(0)
	v_mfma_f32_16x16x32_bf16 v[102:105], v[62:65], v[42:45], 0
	ds_read_b128 v[62:65], v3 offset:8704
	s_waitcnt lgkmcnt(0)
	v_mfma_f32_16x16x32_bf16 v[70:73], v[62:65], v[38:41], 0
	ds_read_b128 v[62:65], v3 offset:8768
	s_waitcnt lgkmcnt(0)
	v_mfma_f32_16x16x32_bf16 v[74:77], v[62:65], v[42:45], 0
	ds_read_b128 v[62:65], v3 offset:13056
	s_nop 0
	v_sub_u32_e32 v3, 0, v109
	v_sub_u32_e32 v78, 1, v109
	v_cvt_f32_i32_e32 v79, v78
	v_cvt_f32_i32_e32 v78, v3
	s_waitcnt lgkmcnt(0)
	v_mfma_f32_16x16x32_bf16 v[62:65], v[62:65], v[38:41], 0
	v_mul_f32_e64 v78, v114, v78
	v_mul_f32_e64 v79, v115, v79
	v_fma_f32 v3, -v114, v117, v78
	v_cndmask_b32_e64 v88, v3, -|v78|, s[24:25]
	v_add_f32_e32 v3, v80, v88
	v_add_f32_e32 v88, v84, v88
	v_fma_f32 v84, -v114, v117, v79
	v_cndmask_b32_e64 v84, v84, -|v79|, s[24:25]
	v_add_f32_e32 v90, v81, v84
	v_add_f32_e32 v89, v85, v84
	v_max_f32_e32 v80, v3, v88
	v_max_f32_e32 v81, v90, v89
	v_max3_f32 v84, v80, s60, v81
	v_sub_u32_e32 v80, 2, v109
	v_sub_u32_e32 v81, 3, v109
	v_cvt_f32_i32_e32 v81, v81
	v_cvt_f32_i32_e32 v80, v80
	v_pk_mul_f32 v[80:81], v[114:115], v[80:81]
	s_nop 0
	v_fma_f32 v85, -v114, v117, v80
	v_cndmask_b32_e64 v85, v85, -|v80|, s[24:25]
	v_add_f32_e32 v92, v82, v85
	v_add_f32_e32 v91, v86, v85
	v_fma_f32 v85, -v114, v117, v81
	v_cndmask_b32_e64 v85, v85, -|v81|, s[24:25]
	v_add_f32_e32 v94, v83, v85
	v_add_f32_e32 v93, v87, v85
	v_max_f32_e32 v82, v92, v91
	v_max_f32_e32 v83, v94, v93
	v_max3_f32 v84, v84, v82, v83
	v_sub_u32_e32 v82, 16, v109
	v_sub_u32_e32 v83, 17, v109
	v_cvt_f32_i32_e32 v83, v83
	v_cvt_f32_i32_e32 v82, v82
	v_pk_mul_f32 v[82:83], v[114:115], v[82:83]
	s_nop 0
	v_fma_f32 v85, -v114, v117, v82
	v_fma_f32 v86, -v114, v117, v83
	v_cndmask_b32_e64 v85, v85, -|v82|, s[24:25]
	v_cndmask_b32_e64 v86, v86, -|v83|, s[24:25]
	v_add_f32_e32 v96, v98, v85
	v_add_f32_e32 v95, v102, v85
	v_add_f32_e32 v98, v99, v86
	v_add_f32_e32 v97, v103, v86
	v_max_f32_e32 v85, v96, v95
	v_max_f32_e32 v86, v98, v97
	v_max3_f32 v86, v84, v85, v86
	v_sub_u32_e32 v84, 18, v109
	v_sub_u32_e32 v85, 19, v109
	v_cvt_f32_i32_e32 v85, v85
	v_cvt_f32_i32_e32 v84, v84
	v_pk_mul_f32 v[84:85], v[114:115], v[84:85]
	s_nop 0
	v_fma_f32 v87, -v114, v117, v84
	v_fma_f32 v102, -v114, v117, v85
	v_cndmask_b32_e64 v87, v87, -|v84|, s[24:25]
	v_cndmask_b32_e64 v103, v102, -|v85|, s[24:25]
	v_add_f32_e32 v100, v100, v87
	v_add_f32_e32 v99, v104, v87
	v_add_f32_e32 v102, v101, v103
	v_add_f32_e32 v101, v105, v103
	v_max_f32_e32 v87, v100, v99
	v_max_f32_e32 v103, v102, v101
	v_max3_f32 v105, v86, v87, v103
	v_sub_u32_e32 v86, 32, v109
	v_sub_u32_e32 v87, 33, v109
	v_cvt_f32_i32_e32 v87, v87
	v_cvt_f32_i32_e32 v86, v86
	v_pk_mul_f32 v[86:87], v[114:115], v[86:87]
	s_nop 0
	v_fma_f32 v103, -v114, v117, v86
	v_cndmask_b32_e64 v104, v103, -|v86|, s[24:25]
	v_add_f32_e32 v103, v70, v104
	v_add_f32_e32 v74, v74, v104
	v_fma_f32 v104, -v114, v117, v87
	v_cndmask_b32_e64 v106, v104, -|v87|, s[24:25]
	v_add_f32_e32 v104, v71, v106
	v_add_f32_e32 v75, v75, v106
	v_max_f32_e32 v70, v103, v74
	v_max_f32_e32 v71, v104, v75
	v_max3_f32 v107, v105, v70, v71
	v_sub_u32_e32 v70, 34, v109
	v_sub_u32_e32 v71, 35, v109
	v_cvt_f32_i32_e32 v71, v71
	v_cvt_f32_i32_e32 v70, v70
	v_pk_mul_f32 v[70:71], v[114:115], v[70:71]
	s_nop 0
	v_fma_f32 v105, -v114, v117, v70
	v_cndmask_b32_e64 v106, v105, -|v70|, s[24:25]
	v_add_f32_e32 v105, v72, v106
	v_add_f32_e32 v76, v76, v106
	v_fma_f32 v106, -v114, v117, v71
	v_cndmask_b32_e64 v108, v106, -|v71|, s[24:25]
	v_add_f32_e32 v106, v73, v108
	v_add_f32_e32 v77, v77, v108
	v_max_f32_e32 v72, v105, v76
	v_max_f32_e32 v73, v106, v77
	v_max3_f32 v158, v107, v72, v73
	v_sub_u32_e32 v72, 48, v109
	v_sub_u32_e32 v73, 49, v109
	v_cvt_f32_i32_e32 v73, v73
	v_cvt_f32_i32_e32 v72, v72
	v_pk_mul_f32 v[72:73], v[114:115], v[72:73]
	s_nop 0
	v_fma_f32 v107, -v114, v117, v72
	v_cndmask_b32_e64 v108, v107, -|v72|, s[24:25]
	v_add_f32_e32 v107, v62, v108
	v_add_f32_e32 v66, v66, v108
	v_fma_f32 v108, -v114, v117, v73
	v_cndmask_b32_e64 v159, v108, -|v73|, s[24:25]
	v_add_f32_e32 v108, v63, v159
	v_add_f32_e32 v67, v67, v159
	v_max_f32_e32 v62, v107, v66
	v_max_f32_e32 v63, v108, v67
	v_max3_f32 v158, v158, v62, v63
	v_sub_u32_e32 v62, 50, v109
	v_sub_u32_e32 v63, 51, v109
	v_cvt_f32_i32_e32 v63, v63
	v_cvt_f32_i32_e32 v62, v62
	v_pk_mul_f32 v[62:63], v[114:115], v[62:63]
	s_nop 0
	v_fma_f32 v109, -v114, v117, v62
	v_cndmask_b32_e64 v159, v109, -|v62|, s[24:25]
	v_add_f32_e32 v109, v64, v159
	v_add_f32_e32 v64, v68, v159
	v_fma_f32 v68, -v114, v117, v63
	v_cndmask_b32_e64 v117, v68, -|v63|, s[24:25]
	v_add_f32_e32 v68, v65, v117
	v_add_f32_e32 v65, v69, v117
	v_max_f32_e32 v159, v109, v64
	v_max_f32_e32 v69, v68, v65
	v_max3_f32 v69, v158, v159, v69
	v_and_b32_e32 v158, 64, v198
	v_mov_b32_e32 v117, v69
	v_mov_b32_e32 v255, v69
	s_nop 1
	v_permlane16_swap_b32_e32 v117, v255
	s_waitcnt lgkmcnt(0)
	v_max_f32_e32 v69, v117, v255
	v_mov_b32_e32 v117, v69
	v_mov_b32_e32 v255, v69
	s_nop 1
	v_permlane32_swap_b32_e32 v117, v255
	s_waitcnt lgkmcnt(0)
	v_max3_f32 v117, v212, v255, v117
	s_cbranch_scc1 .LBB0_1413
	v_sub_f32_e32 v58, v211, v117
	v_pk_add_f32 v[48:49], v[80:81], v[58:59] op_sel_hi:[1,0]
	v_pk_add_f32 v[46:47], v[78:79], v[58:59] op_sel_hi:[1,0]
	v_pk_add_f32 v[52:53], v[84:85], v[58:59] op_sel_hi:[1,0]
	v_pk_add_f32 v[50:51], v[82:83], v[58:59] op_sel_hi:[1,0]
	v_pk_add_f32 v[56:57], v[70:71], v[58:59] op_sel_hi:[1,0]
	v_pk_add_f32 v[54:55], v[86:87], v[58:59] op_sel_hi:[1,0]
	v_pk_add_f32 v[60:61], v[62:63], v[58:59] op_sel_hi:[1,0]
	v_pk_add_f32 v[58:59], v[72:73], v[58:59] op_sel_hi:[1,0]

; __global__ void __launch_bounds__(NTHR, 2) fwd(Args args) {
	.amdhsa_kernel _Z3fwd4Args
		.amdhsa_group_segment_fixed_size 0
		.amdhsa_private_segment_fixed_size 0
		.amdhsa_kernarg_size 696
		.amdhsa_user_sgpr_count 2
		.amdhsa_user_sgpr_dispatch_ptr 0
		.amdhsa_user_sgpr_queue_ptr 0
		.amdhsa_user_sgpr_kernarg_segment_ptr 1
		.amdhsa_user_sgpr_dispatch_id 0
		.amdhsa_user_sgpr_kernarg_preload_length 0
		.amdhsa_user_sgpr_kernarg_preload_offset 0
		.amdhsa_user_sgpr_private_segment_size 0
		.amdhsa_uses_dynamic_stack 0
		.amdhsa_enable_private_segment 0
		.amdhsa_system_sgpr_workgroup_id_x 1
		.amdhsa_system_sgpr_workgroup_id_y 0
		.amdhsa_system_sgpr_workgroup_id_z 0
		.amdhsa_system_sgpr_workgroup_info 0
		.amdhsa_system_vgpr_workitem_id 0
		.amdhsa_next_free_vgpr 256
		.amdhsa_next_free_sgpr 100
		.amdhsa_accum_offset 256
		.amdhsa_reserve_vcc 1
		.amdhsa_float_round_mode_32 0
		.amdhsa_float_round_mode_16_64 0
		.amdhsa_float_denorm_mode_32 3
		.amdhsa_float_denorm_mode_16_64 3
		.amdhsa_dx10_clamp 1
		.amdhsa_ieee_mode 1
		.amdhsa_fp16_overflow 0
		.amdhsa_tg_split 0
		.amdhsa_exception_fp_ieee_invalid_op 0
		.amdhsa_exception_fp_denorm_src 0
		.amdhsa_exception_fp_ieee_div_zero 0
		.amdhsa_exception_fp_ieee_overflow 0
		.amdhsa_exception_fp_ieee_underflow 0
		.amdhsa_exception_fp_ieee_inexact 0
		.amdhsa_exception_int_div_zero 0
	.end_amdhsa_kernel

; __global__ void __launch_bounds__(NTHR, 2) fwd(Args args) {
amdhsa.kernels:
  - .agpr_count:     0
    .args:
      - .offset:         0
        .size:           440
        .value_kind:     by_value
      - .offset:         440
        .size:           4
        .value_kind:     hidden_block_count_x
      - .offset:         444
        .size:           4
        .value_kind:     hidden_block_count_y
      - .offset:         448
        .size:           4
        .value_kind:     hidden_block_count_z
      - .offset:         452
        .size:           2
        .value_kind:     hidden_group_size_x
      - .offset:         454
        .size:           2
        .value_kind:     hidden_group_size_y
      - .offset:         456
        .size:           2
        .value_kind:     hidden_group_size_z
      - .offset:         458
        .size:           2
        .value_kind:     hidden_remainder_x
      - .offset:         460
        .size:           2
        .value_kind:     hidden_remainder_y
      - .offset:         462
        .size:           2
        .value_kind:     hidden_remainder_z
      - .offset:         480
        .size:           8
        .value_kind:     hidden_global_offset_x
      - .offset:         488
        .size:           8
        .value_kind:     hidden_global_offset_y
      - .offset:         496
        .size:           8
        .value_kind:     hidden_global_offset_z
      - .offset:         504
        .size:           2
        .value_kind:     hidden_grid_dims
      - .offset:         560
        .size:           4
        .value_kind:     hidden_dynamic_lds_size
    .group_segment_fixed_size: 0
    .kernarg_segment_align: 8
    .kernarg_segment_size: 696
    .language:       OpenCL C
    .language_version:
      - 2
      - 0
    .max_flat_workgroup_size: 512
    .name:           _Z3fwd4Args
    .private_segment_fixed_size: 0
    .sgpr_count:     106
    .sgpr_spill_count: 400
    .symbol:         _Z3fwd4Args.kd
    .uniform_work_group_size: 1
    .uses_dynamic_stack: false
    .vgpr_count:     256
    .vgpr_spill_count: 0
    .wavefront_size: 64
